# GEMM K-loops: s_setprio 1 of each MMA segment issued before the barrier that opens the segment (56 sites) instead of after it
# speedup vs baseline: 1.0093x; 1.0093x over previous
.LBB0_307:
	v_add_u32_e32 v142, s63, v242
	ds_read_b128 v[130:133], v142
	ds_read_b128 v[134:137], v142 offset:1024
	ds_read_b128 v[138:141], v142 offset:2048
	ds_read_b128 v[142:145], v142 offset:3072
	s_add_i32 s19, s18, 2
	s_add_u32 s20, s14, 0x100
	s_addc_u32 s21, s15, 0
	s_cmp_eq_u32 s24, s18
	s_cselect_b32 s45, s67, s21
	s_cselect_b32 s44, s66, s20
	s_cselect_b32 s35, s71, s26
	s_cselect_b32 s34, s70, s25
	v_lshl_add_u64 v[178:179], s[14:15], 0, v[210:211]
	s_add_i32 m0, s75, 0xc000
	ds_read_b128 v[146:149], v247
	ds_read_b128 v[150:153], v247 offset:1024
	ds_read_b128 v[154:157], v247 offset:2048
	ds_read_b128 v[158:161], v247 offset:3072
	ds_read_b128 v[162:165], v247 offset:4096
	ds_read_b128 v[166:169], v247 offset:5120
	ds_read_b128 v[170:173], v247 offset:6144
	ds_read_b128 v[174:177], v247 offset:7168
	global_load_lds_dwordx4 v[178:179], off
	v_lshl_add_u64 v[178:179], s[14:15], 0, v[212:213]
	s_add_i32 m0, s75, 0xe000
	s_nop 0
	global_load_lds_dwordx4 v[178:179], off
	s_waitcnt lgkmcnt(8)
	s_setprio 1
	s_barrier
	s_waitcnt lgkmcnt(0)
	s_waitcnt lgkmcnt(0)
	v_mfma_f32_16x16x32_bf16 v[126:129], v[130:133], v[146:149], v[126:129]
	v_mfma_f32_16x16x32_bf16 v[122:125], v[138:141], v[146:149], v[122:125]
	v_mfma_f32_16x16x32_bf16 v[118:121], v[130:133], v[154:157], v[118:121]
	v_mfma_f32_16x16x32_bf16 v[114:117], v[138:141], v[154:157], v[114:117]
	v_mfma_f32_16x16x32_bf16 v[110:113], v[130:133], v[162:165], v[110:113]
	v_mfma_f32_16x16x32_bf16 v[106:109], v[138:141], v[162:165], v[106:109]
	v_mfma_f32_16x16x32_bf16 v[102:105], v[130:133], v[170:173], v[102:105]
	v_mfma_f32_16x16x32_bf16 v[98:101], v[138:141], v[170:173], v[98:101]
	v_mfma_f32_16x16x32_bf16 v[126:129], v[134:137], v[150:153], v[126:129]
	v_mfma_f32_16x16x32_bf16 v[122:125], v[142:145], v[150:153], v[122:125]
	v_mfma_f32_16x16x32_bf16 v[118:121], v[134:137], v[158:161], v[118:121]
	v_mfma_f32_16x16x32_bf16 v[114:117], v[142:145], v[158:161], v[114:117]
	v_mfma_f32_16x16x32_bf16 v[110:113], v[134:137], v[166:169], v[110:113]
	v_mfma_f32_16x16x32_bf16 v[106:109], v[142:145], v[166:169], v[106:109]
	v_mfma_f32_16x16x32_bf16 v[102:105], v[134:137], v[174:177], v[102:105]
	v_mfma_f32_16x16x32_bf16 v[98:101], v[142:145], v[174:177], v[98:101]
	s_setprio 0
	s_barrier
	s_mov_b32 m0, s73
	v_add_u32_e32 v194, s77, v242
	v_lshl_add_u64 v[214:215], s[34:35], 0, v[0:1]
	ds_read_b128 v[178:181], v194
	ds_read_b128 v[182:185], v194 offset:1024
	ds_read_b128 v[186:189], v194 offset:2048
	ds_read_b128 v[194:197], v194 offset:3072
	global_load_lds_dwordx4 v[214:215], off
	v_lshl_add_u64 v[216:217], s[34:35], 0, v[204:205]
	s_mov_b32 m0, s74
	s_nop 0
	global_load_lds_dwordx4 v[216:217], off
	s_setprio 1
	s_barrier
	s_waitcnt lgkmcnt(0)
	s_waitcnt lgkmcnt(0)
	v_mfma_f32_16x16x32_bf16 v[94:97], v[178:181], v[146:149], v[94:97]
	v_mfma_f32_16x16x32_bf16 v[90:93], v[186:189], v[146:149], v[90:93]
	v_mfma_f32_16x16x32_bf16 v[86:89], v[178:181], v[154:157], v[86:89]
	v_mfma_f32_16x16x32_bf16 v[82:85], v[186:189], v[154:157], v[82:85]
	v_mfma_f32_16x16x32_bf16 v[78:81], v[178:181], v[162:165], v[78:81]
	v_mfma_f32_16x16x32_bf16 v[74:77], v[186:189], v[162:165], v[74:77]
	v_mfma_f32_16x16x32_bf16 v[70:73], v[178:181], v[170:173], v[70:73]
	v_mfma_f32_16x16x32_bf16 v[66:69], v[186:189], v[170:173], v[66:69]
	v_mfma_f32_16x16x32_bf16 v[94:97], v[182:185], v[150:153], v[94:97]
	v_mfma_f32_16x16x32_bf16 v[90:93], v[194:197], v[150:153], v[90:93]
	v_mfma_f32_16x16x32_bf16 v[86:89], v[182:185], v[158:161], v[86:89]
	v_mfma_f32_16x16x32_bf16 v[82:85], v[194:197], v[158:161], v[82:85]
	v_mfma_f32_16x16x32_bf16 v[78:81], v[182:185], v[166:169], v[78:81]
	v_mfma_f32_16x16x32_bf16 v[74:77], v[194:197], v[166:169], v[74:77]
	v_mfma_f32_16x16x32_bf16 v[70:73], v[182:185], v[174:177], v[70:73]
	v_mfma_f32_16x16x32_bf16 v[66:69], v[194:197], v[174:177], v[66:69]
	s_setprio 0
	s_mov_b32 m0, s75
	v_lshl_add_u64 v[218:219], s[44:45], 0, v[0:1]
	s_barrier
	ds_read_b128 v[146:149], v247 offset:16384
	ds_read_b128 v[150:153], v247 offset:17408
	ds_read_b128 v[154:157], v247 offset:18432
	ds_read_b128 v[158:161], v247 offset:19456
	ds_read_b128 v[162:165], v247 offset:20480
	ds_read_b128 v[166:169], v247 offset:21504
	ds_read_b128 v[170:173], v247 offset:22528
	ds_read_b128 v[174:177], v247 offset:23552
	global_load_lds_dwordx4 v[218:219], off
	v_lshl_add_u64 v[220:221], s[44:45], 0, v[204:205]
	s_mov_b32 m0, s76
	s_nop 0
	global_load_lds_dwordx4 v[220:221], off
	s_setprio 1
	s_barrier
	s_waitcnt lgkmcnt(0)
	s_waitcnt lgkmcnt(0)
	v_mfma_f32_16x16x32_bf16 v[62:65], v[130:133], v[146:149], v[62:65]
	v_mfma_f32_16x16x32_bf16 v[58:61], v[138:141], v[146:149], v[58:61]
	v_mfma_f32_16x16x32_bf16 v[54:57], v[130:133], v[154:157], v[54:57]
	v_mfma_f32_16x16x32_bf16 v[50:53], v[138:141], v[154:157], v[50:53]
	v_mfma_f32_16x16x32_bf16 v[46:49], v[130:133], v[162:165], v[46:49]
	v_mfma_f32_16x16x32_bf16 v[42:45], v[138:141], v[162:165], v[42:45]
	v_mfma_f32_16x16x32_bf16 v[38:41], v[130:133], v[170:173], v[38:41]
	v_mfma_f32_16x16x32_bf16 v[34:37], v[138:141], v[170:173], v[34:37]
	v_mfma_f32_16x16x32_bf16 v[62:65], v[134:137], v[150:153], v[62:65]
	v_mfma_f32_16x16x32_bf16 v[58:61], v[142:145], v[150:153], v[58:61]
	v_mfma_f32_16x16x32_bf16 v[54:57], v[134:137], v[158:161], v[54:57]
	v_mfma_f32_16x16x32_bf16 v[50:53], v[142:145], v[158:161], v[50:53]
	v_mfma_f32_16x16x32_bf16 v[46:49], v[134:137], v[166:169], v[46:49]
	v_mfma_f32_16x16x32_bf16 v[42:45], v[142:145], v[166:169], v[42:45]
	v_mfma_f32_16x16x32_bf16 v[38:41], v[134:137], v[174:177], v[38:41]
	v_mfma_f32_16x16x32_bf16 v[34:37], v[142:145], v[174:177], v[34:37]
	s_setprio 0
	s_barrier
	s_add_u32 s0, s34, 0xb0000
	s_addc_u32 s1, s35, 0
	s_mov_b32 m0, s78
	v_lshl_add_u64 v[130:131], s[0:1], 0, v[0:1]
	global_load_lds_dwordx4 v[130:131], off
	v_lshl_add_u64 v[130:131], s[0:1], 0, v[204:205]
	s_mov_b32 m0, s79
	s_nop 0
	global_load_lds_dwordx4 v[130:131], off
	s_waitcnt vmcnt(6)
	s_setprio 1
	s_barrier
	v_mfma_f32_16x16x32_bf16 v[30:33], v[178:181], v[146:149], v[30:33]
	v_mfma_f32_16x16x32_bf16 v[26:29], v[186:189], v[146:149], v[26:29]
	v_mfma_f32_16x16x32_bf16 v[22:25], v[178:181], v[154:157], v[22:25]
	v_mfma_f32_16x16x32_bf16 v[18:21], v[186:189], v[154:157], v[18:21]
	v_mfma_f32_16x16x32_bf16 v[14:17], v[178:181], v[162:165], v[14:17]
	v_mfma_f32_16x16x32_bf16 v[10:13], v[186:189], v[162:165], v[10:13]
	v_mfma_f32_16x16x32_bf16 v[6:9], v[178:181], v[170:173], v[6:9]
	v_mfma_f32_16x16x32_bf16 v[2:5], v[186:189], v[170:173], v[2:5]
	v_mfma_f32_16x16x32_bf16 v[30:33], v[182:185], v[150:153], v[30:33]
	v_mfma_f32_16x16x32_bf16 v[26:29], v[194:197], v[150:153], v[26:29]
	v_mfma_f32_16x16x32_bf16 v[22:25], v[182:185], v[158:161], v[22:25]
	v_mfma_f32_16x16x32_bf16 v[18:21], v[194:197], v[158:161], v[18:21]
	v_mfma_f32_16x16x32_bf16 v[14:17], v[182:185], v[166:169], v[14:17]
	v_mfma_f32_16x16x32_bf16 v[10:13], v[194:197], v[166:169], v[10:13]
	v_mfma_f32_16x16x32_bf16 v[6:9], v[182:185], v[174:177], v[6:9]
	v_mfma_f32_16x16x32_bf16 v[2:5], v[194:197], v[174:177], v[2:5]
	s_setprio 0
	v_add_u32_e32 v142, s94, v242
	s_barrier
	ds_read_b128 v[130:133], v142
	ds_read_b128 v[134:137], v142 offset:1024
	ds_read_b128 v[138:141], v142 offset:2048
	ds_read_b128 v[142:145], v142 offset:3072
	s_add_u32 s0, s44, 0xb0000
	s_addc_u32 s1, s45, 0
	s_mov_b32 m0, s80
	v_lshl_add_u64 v[178:179], s[0:1], 0, v[0:1]
	ds_read_b128 v[146:149], v247 offset:32768
	ds_read_b128 v[150:153], v247 offset:33792
	ds_read_b128 v[154:157], v247 offset:34816
	ds_read_b128 v[158:161], v247 offset:35840
	ds_read_b128 v[162:165], v247 offset:36864
	ds_read_b128 v[166:169], v247 offset:37888
	ds_read_b128 v[170:173], v247 offset:38912
	ds_read_b128 v[174:177], v247 offset:39936
	global_load_lds_dwordx4 v[178:179], off
	v_lshl_add_u64 v[178:179], s[0:1], 0, v[204:205]
	s_mov_b32 m0, s81
	s_nop 0
	global_load_lds_dwordx4 v[178:179], off
	s_waitcnt lgkmcnt(8)
	s_setprio 1
	s_barrier
	s_waitcnt lgkmcnt(0)
	s_waitcnt lgkmcnt(0)
	v_mfma_f32_16x16x32_bf16 v[126:129], v[130:133], v[146:149], v[126:129]
	v_mfma_f32_16x16x32_bf16 v[122:125], v[138:141], v[146:149], v[122:125]
	v_mfma_f32_16x16x32_bf16 v[118:121], v[130:133], v[154:157], v[118:121]
	v_mfma_f32_16x16x32_bf16 v[114:117], v[138:141], v[154:157], v[114:117]
	v_mfma_f32_16x16x32_bf16 v[110:113], v[130:133], v[162:165], v[110:113]
	v_mfma_f32_16x16x32_bf16 v[106:109], v[138:141], v[162:165], v[106:109]
	v_mfma_f32_16x16x32_bf16 v[102:105], v[130:133], v[170:173], v[102:105]
	v_mfma_f32_16x16x32_bf16 v[98:101], v[138:141], v[170:173], v[98:101]
	v_mfma_f32_16x16x32_bf16 v[126:129], v[134:137], v[150:153], v[126:129]
	v_mfma_f32_16x16x32_bf16 v[122:125], v[142:145], v[150:153], v[122:125]
	v_mfma_f32_16x16x32_bf16 v[118:121], v[134:137], v[158:161], v[118:121]
	v_mfma_f32_16x16x32_bf16 v[114:117], v[142:145], v[158:161], v[114:117]
	v_mfma_f32_16x16x32_bf16 v[110:113], v[134:137], v[166:169], v[110:113]
	v_mfma_f32_16x16x32_bf16 v[106:109], v[142:145], v[166:169], v[106:109]
	v_mfma_f32_16x16x32_bf16 v[102:105], v[134:137], v[174:177], v[102:105]
	v_mfma_f32_16x16x32_bf16 v[98:101], v[142:145], v[174:177], v[98:101]
	s_setprio 0
	s_barrier
	s_mov_b32 m0, s95
	v_add_u32_e32 v194, s37, v242
	v_lshl_add_u64 v[214:215], v[214:215], 0, s[88:89]
	ds_read_b128 v[178:181], v194
	ds_read_b128 v[182:185], v194 offset:1024
	ds_read_b128 v[186:189], v194 offset:2048
	ds_read_b128 v[194:197], v194 offset:3072
	global_load_lds_dwordx4 v[214:215], off
	v_lshl_add_u64 v[214:215], v[216:217], 0, s[88:89]
	s_mov_b32 m0, s16
	s_nop 0
	global_load_lds_dwordx4 v[214:215], off
	s_setprio 1
	s_barrier
	s_waitcnt lgkmcnt(0)
	s_waitcnt lgkmcnt(0)
	v_mfma_f32_16x16x32_bf16 v[94:97], v[178:181], v[146:149], v[94:97]
	v_mfma_f32_16x16x32_bf16 v[90:93], v[186:189], v[146:149], v[90:93]
	v_mfma_f32_16x16x32_bf16 v[86:89], v[178:181], v[154:157], v[86:89]
	v_mfma_f32_16x16x32_bf16 v[82:85], v[186:189], v[154:157], v[82:85]
	v_mfma_f32_16x16x32_bf16 v[78:81], v[178:181], v[162:165], v[78:81]
	v_mfma_f32_16x16x32_bf16 v[74:77], v[186:189], v[162:165], v[74:77]
	v_mfma_f32_16x16x32_bf16 v[70:73], v[178:181], v[170:173], v[70:73]
	v_mfma_f32_16x16x32_bf16 v[66:69], v[186:189], v[170:173], v[66:69]
	v_mfma_f32_16x16x32_bf16 v[94:97], v[182:185], v[150:153], v[94:97]
	v_mfma_f32_16x16x32_bf16 v[90:93], v[194:197], v[150:153], v[90:93]
	v_mfma_f32_16x16x32_bf16 v[86:89], v[182:185], v[158:161], v[86:89]
	v_mfma_f32_16x16x32_bf16 v[82:85], v[194:197], v[158:161], v[82:85]
	v_mfma_f32_16x16x32_bf16 v[78:81], v[182:185], v[166:169], v[78:81]
	v_mfma_f32_16x16x32_bf16 v[74:77], v[194:197], v[166:169], v[74:77]
	v_mfma_f32_16x16x32_bf16 v[70:73], v[182:185], v[174:177], v[70:73]
	v_mfma_f32_16x16x32_bf16 v[66:69], v[194:197], v[174:177], v[66:69]
	s_setprio 0
	s_mov_b32 m0, s17
	v_lshl_add_u64 v[214:215], v[218:219], 0, s[88:89]
	s_barrier
	ds_read_b128 v[146:149], v247 offset:49152
	ds_read_b128 v[150:153], v247 offset:50176
	ds_read_b128 v[154:157], v247 offset:51200
	ds_read_b128 v[158:161], v247 offset:52224
	ds_read_b128 v[162:165], v247 offset:53248
	ds_read_b128 v[166:169], v247 offset:54272
	ds_read_b128 v[170:173], v247 offset:55296
	ds_read_b128 v[174:177], v247 offset:56320
	global_load_lds_dwordx4 v[214:215], off
	v_lshl_add_u64 v[214:215], v[220:221], 0, s[88:89]
	s_mov_b32 m0, s60
	s_nop 0
	global_load_lds_dwordx4 v[214:215], off
	s_setprio 1
	s_barrier
	s_waitcnt lgkmcnt(0)
	s_waitcnt lgkmcnt(0)
	v_mfma_f32_16x16x32_bf16 v[62:65], v[130:133], v[146:149], v[62:65]
	v_mfma_f32_16x16x32_bf16 v[58:61], v[138:141], v[146:149], v[58:61]
	v_mfma_f32_16x16x32_bf16 v[54:57], v[130:133], v[154:157], v[54:57]
	v_mfma_f32_16x16x32_bf16 v[50:53], v[138:141], v[154:157], v[50:53]
	v_mfma_f32_16x16x32_bf16 v[46:49], v[130:133], v[162:165], v[46:49]
	v_mfma_f32_16x16x32_bf16 v[42:45], v[138:141], v[162:165], v[42:45]
	v_mfma_f32_16x16x32_bf16 v[38:41], v[130:133], v[170:173], v[38:41]
	v_mfma_f32_16x16x32_bf16 v[34:37], v[138:141], v[170:173], v[34:37]
	v_mfma_f32_16x16x32_bf16 v[62:65], v[134:137], v[150:153], v[62:65]
	v_mfma_f32_16x16x32_bf16 v[58:61], v[142:145], v[150:153], v[58:61]
	v_mfma_f32_16x16x32_bf16 v[54:57], v[134:137], v[158:161], v[54:57]
	v_mfma_f32_16x16x32_bf16 v[50:53], v[142:145], v[158:161], v[50:53]
	v_mfma_f32_16x16x32_bf16 v[46:49], v[134:137], v[166:169], v[46:49]
	v_mfma_f32_16x16x32_bf16 v[42:45], v[142:145], v[166:169], v[42:45]
	v_mfma_f32_16x16x32_bf16 v[38:41], v[134:137], v[174:177], v[38:41]
	v_mfma_f32_16x16x32_bf16 v[34:37], v[142:145], v[174:177], v[34:37]
	s_setprio 0
	s_barrier
	s_add_u32 s0, s34, 0xb0080
	s_addc_u32 s1, s35, 0
	s_mov_b32 m0, s2
	v_lshl_add_u64 v[130:131], s[0:1], 0, v[0:1]
	global_load_lds_dwordx4 v[130:131], off
	v_lshl_add_u64 v[130:131], s[0:1], 0, v[204:205]
	s_mov_b32 m0, s3
	s_nop 0
	global_load_lds_dwordx4 v[130:131], off
	s_waitcnt vmcnt(6)
	s_setprio 1
	s_barrier
	v_mfma_f32_16x16x32_bf16 v[30:33], v[178:181], v[146:149], v[30:33]
	v_mfma_f32_16x16x32_bf16 v[26:29], v[186:189], v[146:149], v[26:29]
	v_mfma_f32_16x16x32_bf16 v[22:25], v[178:181], v[154:157], v[22:25]
	v_mfma_f32_16x16x32_bf16 v[18:21], v[186:189], v[154:157], v[18:21]
	v_mfma_f32_16x16x32_bf16 v[14:17], v[178:181], v[162:165], v[14:17]
	v_mfma_f32_16x16x32_bf16 v[10:13], v[186:189], v[162:165], v[10:13]
	v_mfma_f32_16x16x32_bf16 v[6:9], v[178:181], v[170:173], v[6:9]
	v_mfma_f32_16x16x32_bf16 v[2:5], v[186:189], v[170:173], v[2:5]
	v_mfma_f32_16x16x32_bf16 v[30:33], v[182:185], v[150:153], v[30:33]
	v_mfma_f32_16x16x32_bf16 v[26:29], v[194:197], v[150:153], v[26:29]
	v_mfma_f32_16x16x32_bf16 v[22:25], v[182:185], v[158:161], v[22:25]
	v_mfma_f32_16x16x32_bf16 v[18:21], v[194:197], v[158:161], v[18:21]
	v_mfma_f32_16x16x32_bf16 v[14:17], v[182:185], v[166:169], v[14:17]
	v_mfma_f32_16x16x32_bf16 v[10:13], v[194:197], v[166:169], v[10:13]
	v_mfma_f32_16x16x32_bf16 v[6:9], v[182:185], v[174:177], v[6:9]
	v_mfma_f32_16x16x32_bf16 v[2:5], v[194:197], v[174:177], v[2:5]
	s_setprio 0
	s_add_u32 s25, s25, 0x100
	s_addc_u32 s26, s26, 0
	s_cmp_ge_i32 s19, s11
	s_mov_b64 s[14:15], s[20:21]
	s_mov_b32 s18, s19
	s_barrier
	s_cbranch_scc0 .LBB0_307
	v_readfirstlane_b32 s98, v191
	s_cmpk_gt_u32 s98, 0xff
	s_cbranch_scc1 .Lrl_e0_307
	s_barrier

.LBB0_705:
	v_add_u32_e32 v86, s61, v184
	ds_read_b128 v[74:77], v86
	ds_read_b128 v[78:81], v86 offset:1024
	ds_read_b128 v[82:85], v86 offset:2048
	ds_read_b128 v[86:89], v86 offset:3072
	s_add_u32 s0, s20, 0xfffc0080
	s_addc_u32 s1, s21, -1
	s_cmp_eq_u32 vcc_lo, 12
	s_cselect_b32 s51, s49, s1
	s_cselect_b32 s50, s53, s0
	s_cselect_b32 s35, s54, s95
	s_cselect_b32 s34, s55, s93
	v_lshl_add_u64 v[180:181], s[20:21], 0, v[172:173]
	s_add_i32 m0, s85, 0xc000
	ds_read_b128 v[146:149], v201
	ds_read_b128 v[150:153], v201 offset:1024
	ds_read_b128 v[154:157], v201 offset:2048
	ds_read_b128 v[158:161], v201 offset:3072
	ds_read_b128 v[162:165], v201 offset:4096
	ds_read_b128 v[166:169], v201 offset:5120
	ds_read_b128 v[176:179], v201 offset:6144
	ds_read_b128 v[194:197], v201 offset:7168
	global_load_lds_dwordx4 v[180:181], off
	v_lshl_add_u64 v[180:181], s[20:21], 0, v[174:175]
	s_add_i32 m0, s85, 0xe000
	s_nop 0
	global_load_lds_dwordx4 v[180:181], off
	s_waitcnt lgkmcnt(8)
	s_setprio 1
	s_barrier
	s_waitcnt lgkmcnt(0)
	s_waitcnt lgkmcnt(0)
	v_mfma_f32_16x16x32_bf16 v[126:129], v[74:77], v[146:149], v[126:129]
	v_mfma_f32_16x16x32_bf16 v[46:49], v[82:85], v[146:149], v[46:49]
	v_mfma_f32_16x16x32_bf16 v[138:141], v[74:77], v[154:157], v[138:141]
	v_mfma_f32_16x16x32_bf16 v[58:61], v[82:85], v[154:157], v[58:61]
	v_mfma_f32_16x16x32_bf16 v[130:133], v[74:77], v[162:165], v[130:133]
	v_mfma_f32_16x16x32_bf16 v[50:53], v[82:85], v[162:165], v[50:53]
	v_mfma_f32_16x16x32_bf16 v[114:117], v[74:77], v[176:179], v[114:117]
	v_mfma_f32_16x16x32_bf16 v[34:37], v[82:85], v[176:179], v[34:37]
	v_mfma_f32_16x16x32_bf16 v[126:129], v[78:81], v[150:153], v[126:129]
	v_mfma_f32_16x16x32_bf16 v[46:49], v[86:89], v[150:153], v[46:49]
	v_mfma_f32_16x16x32_bf16 v[138:141], v[78:81], v[158:161], v[138:141]
	v_mfma_f32_16x16x32_bf16 v[58:61], v[86:89], v[158:161], v[58:61]
	v_mfma_f32_16x16x32_bf16 v[130:133], v[78:81], v[166:169], v[130:133]
	v_mfma_f32_16x16x32_bf16 v[50:53], v[86:89], v[166:169], v[50:53]
	v_mfma_f32_16x16x32_bf16 v[114:117], v[78:81], v[194:197], v[114:117]
	v_mfma_f32_16x16x32_bf16 v[34:37], v[86:89], v[194:197], v[34:37]
	s_setprio 0
	s_barrier
	v_add_u32_e32 v180, s19, v184
	s_mov_b32 m0, s62
	ds_read_b128 v[204:207], v180
	ds_read_b128 v[208:211], v180 offset:1024
	ds_read_b128 v[212:215], v180 offset:2048
	ds_read_b128 v[216:219], v180 offset:3072
	v_lshl_add_u64 v[180:181], s[34:35], 0, v[0:1]
	global_load_lds_dwordx4 v[180:181], off
	v_lshl_add_u64 v[220:221], s[34:35], 0, v[170:171]
	s_mov_b32 m0, s63
	s_nop 0
	global_load_lds_dwordx4 v[220:221], off
	s_setprio 1
	s_barrier
	s_waitcnt lgkmcnt(0)
	s_waitcnt lgkmcnt(0)
	v_mfma_f32_16x16x32_bf16 v[142:145], v[204:207], v[146:149], v[142:145]
	v_mfma_f32_16x16x32_bf16 v[62:65], v[212:215], v[146:149], v[62:65]
	v_mfma_f32_16x16x32_bf16 v[134:137], v[204:207], v[154:157], v[134:137]
	v_mfma_f32_16x16x32_bf16 v[54:57], v[212:215], v[154:157], v[54:57]
	v_mfma_f32_16x16x32_bf16 v[122:125], v[204:207], v[162:165], v[122:125]
	v_mfma_f32_16x16x32_bf16 v[42:45], v[212:215], v[162:165], v[42:45]
	v_mfma_f32_16x16x32_bf16 v[118:121], v[204:207], v[176:179], v[118:121]
	v_mfma_f32_16x16x32_bf16 v[38:41], v[212:215], v[176:179], v[38:41]
	v_mfma_f32_16x16x32_bf16 v[142:145], v[208:211], v[150:153], v[142:145]
	v_mfma_f32_16x16x32_bf16 v[62:65], v[216:219], v[150:153], v[62:65]
	v_mfma_f32_16x16x32_bf16 v[134:137], v[208:211], v[158:161], v[134:137]
	v_mfma_f32_16x16x32_bf16 v[54:57], v[216:219], v[158:161], v[54:57]
	v_mfma_f32_16x16x32_bf16 v[122:125], v[208:211], v[166:169], v[122:125]
	v_mfma_f32_16x16x32_bf16 v[42:45], v[216:219], v[166:169], v[42:45]
	v_mfma_f32_16x16x32_bf16 v[118:121], v[208:211], v[194:197], v[118:121]
	v_mfma_f32_16x16x32_bf16 v[38:41], v[216:219], v[194:197], v[38:41]
	s_setprio 0
	s_mov_b32 m0, s85
	v_lshl_add_u64 v[222:223], s[50:51], 0, v[0:1]
	s_barrier
	ds_read_b128 v[146:149], v201 offset:16384
	ds_read_b128 v[150:153], v201 offset:17408
	ds_read_b128 v[154:157], v201 offset:18432
	ds_read_b128 v[158:161], v201 offset:19456
	ds_read_b128 v[162:165], v201 offset:20480
	ds_read_b128 v[166:169], v201 offset:21504
	ds_read_b128 v[176:179], v201 offset:22528
	ds_read_b128 v[194:197], v201 offset:23552
	global_load_lds_dwordx4 v[222:223], off
	v_lshl_add_u64 v[232:233], s[50:51], 0, v[170:171]
	s_mov_b32 m0, s86
	s_nop 0
	global_load_lds_dwordx4 v[232:233], off
	s_setprio 1
	s_barrier
	s_waitcnt lgkmcnt(0)
	s_waitcnt lgkmcnt(0)
	v_mfma_f32_16x16x32_bf16 v[106:109], v[74:77], v[146:149], v[106:109]
	v_mfma_f32_16x16x32_bf16 v[30:33], v[82:85], v[146:149], v[30:33]
	v_mfma_f32_16x16x32_bf16 v[102:105], v[74:77], v[154:157], v[102:105]
	v_mfma_f32_16x16x32_bf16 v[22:25], v[82:85], v[154:157], v[22:25]
	v_mfma_f32_16x16x32_bf16 v[94:97], v[74:77], v[162:165], v[94:97]
	v_mfma_f32_16x16x32_bf16 v[14:17], v[82:85], v[162:165], v[14:17]
	v_mfma_f32_16x16x32_bf16 v[66:69], v[74:77], v[176:179], v[66:69]
	v_mfma_f32_16x16x32_bf16 v[2:5], v[82:85], v[176:179], v[2:5]
	v_mfma_f32_16x16x32_bf16 v[106:109], v[78:81], v[150:153], v[106:109]
	v_mfma_f32_16x16x32_bf16 v[30:33], v[86:89], v[150:153], v[30:33]
	v_mfma_f32_16x16x32_bf16 v[102:105], v[78:81], v[158:161], v[102:105]
	v_mfma_f32_16x16x32_bf16 v[22:25], v[86:89], v[158:161], v[22:25]
	v_mfma_f32_16x16x32_bf16 v[94:97], v[78:81], v[166:169], v[94:97]
	v_mfma_f32_16x16x32_bf16 v[14:17], v[86:89], v[166:169], v[14:17]
	v_mfma_f32_16x16x32_bf16 v[66:69], v[78:81], v[194:197], v[66:69]
	v_mfma_f32_16x16x32_bf16 v[2:5], v[86:89], v[194:197], v[2:5]
	s_setprio 0
	s_barrier
	s_add_u32 s0, s34, 0x40000
	s_addc_u32 s1, s35, 0
	s_mov_b32 m0, s90
	v_lshl_add_u64 v[74:75], s[0:1], 0, v[0:1]
	global_load_lds_dwordx4 v[74:75], off
	v_lshl_add_u64 v[74:75], s[0:1], 0, v[170:171]
	s_mov_b32 m0, s26
	s_nop 0
	global_load_lds_dwordx4 v[74:75], off
	s_waitcnt vmcnt(6)
	s_setprio 1
	s_barrier
	v_mfma_f32_16x16x32_bf16 v[26:29], v[212:215], v[146:149], v[26:29]
	v_mfma_f32_16x16x32_bf16 v[18:21], v[212:215], v[154:157], v[18:21]
	v_mfma_f32_16x16x32_bf16 v[10:13], v[212:215], v[162:165], v[10:13]
	v_mfma_f32_16x16x32_bf16 v[70:73], v[204:207], v[176:179], v[70:73]
	v_mfma_f32_16x16x32_bf16 v[6:9], v[212:215], v[176:179], v[6:9]
	v_mfma_f32_16x16x32_bf16 v[74:77], v[204:207], v[146:149], v[110:113]
	v_mfma_f32_16x16x32_bf16 v[26:29], v[216:219], v[150:153], v[26:29]
	v_mfma_f32_16x16x32_bf16 v[78:81], v[204:207], v[154:157], v[98:101]
	v_mfma_f32_16x16x32_bf16 v[18:21], v[216:219], v[158:161], v[18:21]
	v_mfma_f32_16x16x32_bf16 v[82:85], v[204:207], v[162:165], v[90:93]
	v_mfma_f32_16x16x32_bf16 v[10:13], v[216:219], v[166:169], v[10:13]
	v_mfma_f32_16x16x32_bf16 v[70:73], v[208:211], v[194:197], v[70:73]
	v_mfma_f32_16x16x32_bf16 v[6:9], v[216:219], v[194:197], v[6:9]
	v_mfma_f32_16x16x32_bf16 v[74:77], v[208:211], v[150:153], v[74:77]
	v_mfma_f32_16x16x32_bf16 v[78:81], v[208:211], v[158:161], v[78:81]
	v_mfma_f32_16x16x32_bf16 v[82:85], v[208:211], v[166:169], v[82:85]
	s_setprio 0
	v_add_u32_e32 v110, s36, v184
	s_barrier
	ds_read_b128 v[86:89], v110
	ds_read_b128 v[90:93], v110 offset:1024
	ds_read_b128 v[98:101], v110 offset:2048
	ds_read_b128 v[110:113], v110 offset:3072
	s_add_u32 s0, s50, 0x40000
	s_addc_u32 s1, s51, 0
	s_mov_b32 m0, s28
	v_lshl_add_u64 v[204:205], s[0:1], 0, v[0:1]
	ds_read_b128 v[146:149], v201 offset:32768
	ds_read_b128 v[150:153], v201 offset:33792
	ds_read_b128 v[154:157], v201 offset:34816
	ds_read_b128 v[158:161], v201 offset:35840
	ds_read_b128 v[162:165], v201 offset:36864
	ds_read_b128 v[166:169], v201 offset:37888
	ds_read_b128 v[176:179], v201 offset:38912
	ds_read_b128 v[194:197], v201 offset:39936
	global_load_lds_dwordx4 v[204:205], off
	v_lshl_add_u64 v[204:205], s[0:1], 0, v[170:171]
	s_mov_b32 m0, s30
	s_nop 0
	global_load_lds_dwordx4 v[204:205], off
	s_waitcnt lgkmcnt(8)
	s_setprio 1
	s_barrier
	s_waitcnt lgkmcnt(0)
	s_waitcnt lgkmcnt(0)
	v_mfma_f32_16x16x32_bf16 v[126:129], v[86:89], v[146:149], v[126:129]
	v_mfma_f32_16x16x32_bf16 v[46:49], v[98:101], v[146:149], v[46:49]
	v_mfma_f32_16x16x32_bf16 v[138:141], v[86:89], v[154:157], v[138:141]
	v_mfma_f32_16x16x32_bf16 v[58:61], v[98:101], v[154:157], v[58:61]
	v_mfma_f32_16x16x32_bf16 v[130:133], v[86:89], v[162:165], v[130:133]
	v_mfma_f32_16x16x32_bf16 v[50:53], v[98:101], v[162:165], v[50:53]
	v_mfma_f32_16x16x32_bf16 v[114:117], v[86:89], v[176:179], v[114:117]
	v_mfma_f32_16x16x32_bf16 v[34:37], v[98:101], v[176:179], v[34:37]
	v_mfma_f32_16x16x32_bf16 v[126:129], v[90:93], v[150:153], v[126:129]
	v_mfma_f32_16x16x32_bf16 v[46:49], v[110:113], v[150:153], v[46:49]
	v_mfma_f32_16x16x32_bf16 v[138:141], v[90:93], v[158:161], v[138:141]
	v_mfma_f32_16x16x32_bf16 v[58:61], v[110:113], v[158:161], v[58:61]
	v_mfma_f32_16x16x32_bf16 v[130:133], v[90:93], v[166:169], v[130:133]
	v_mfma_f32_16x16x32_bf16 v[50:53], v[110:113], v[166:169], v[50:53]
	v_mfma_f32_16x16x32_bf16 v[114:117], v[90:93], v[194:197], v[114:117]
	v_mfma_f32_16x16x32_bf16 v[34:37], v[110:113], v[194:197], v[34:37]
	s_setprio 0
	s_barrier
	s_mov_b32 m0, s58
	v_add_u32_e32 v216, s8, v184
	v_lshl_add_u64 v[180:181], v[180:181], 0, s[88:89]
	ds_read_b128 v[204:207], v216
	ds_read_b128 v[208:211], v216 offset:1024
	ds_read_b128 v[212:215], v216 offset:2048
	ds_read_b128 v[216:219], v216 offset:3072
	global_load_lds_dwordx4 v[180:181], off
	v_lshl_add_u64 v[180:181], v[220:221], 0, s[88:89]
	s_mov_b32 m0, s38
	s_nop 0
	global_load_lds_dwordx4 v[180:181], off
	s_setprio 1
	s_barrier
	s_waitcnt lgkmcnt(0)
	s_waitcnt lgkmcnt(0)
	v_mfma_f32_16x16x32_bf16 v[142:145], v[204:207], v[146:149], v[142:145]
	v_mfma_f32_16x16x32_bf16 v[62:65], v[212:215], v[146:149], v[62:65]
	v_mfma_f32_16x16x32_bf16 v[134:137], v[204:207], v[154:157], v[134:137]
	v_mfma_f32_16x16x32_bf16 v[54:57], v[212:215], v[154:157], v[54:57]
	v_mfma_f32_16x16x32_bf16 v[122:125], v[204:207], v[162:165], v[122:125]
	v_mfma_f32_16x16x32_bf16 v[42:45], v[212:215], v[162:165], v[42:45]
	v_mfma_f32_16x16x32_bf16 v[118:121], v[204:207], v[176:179], v[118:121]
	v_mfma_f32_16x16x32_bf16 v[38:41], v[212:215], v[176:179], v[38:41]
	v_mfma_f32_16x16x32_bf16 v[142:145], v[208:211], v[150:153], v[142:145]
	v_mfma_f32_16x16x32_bf16 v[62:65], v[216:219], v[150:153], v[62:65]
	v_mfma_f32_16x16x32_bf16 v[134:137], v[208:211], v[158:161], v[134:137]
	v_mfma_f32_16x16x32_bf16 v[54:57], v[216:219], v[158:161], v[54:57]
	v_mfma_f32_16x16x32_bf16 v[122:125], v[208:211], v[166:169], v[122:125]
	v_mfma_f32_16x16x32_bf16 v[42:45], v[216:219], v[166:169], v[42:45]
	v_mfma_f32_16x16x32_bf16 v[118:121], v[208:211], v[194:197], v[118:121]
	v_mfma_f32_16x16x32_bf16 v[38:41], v[216:219], v[194:197], v[38:41]
	s_setprio 0
	s_mov_b32 m0, s96
	v_lshl_add_u64 v[180:181], v[222:223], 0, s[88:89]
	s_barrier
	ds_read_b128 v[146:149], v201 offset:49152
	ds_read_b128 v[150:153], v201 offset:50176
	ds_read_b128 v[154:157], v201 offset:51200
	ds_read_b128 v[158:161], v201 offset:52224
	ds_read_b128 v[162:165], v201 offset:53248
	ds_read_b128 v[166:169], v201 offset:54272
	ds_read_b128 v[176:179], v201 offset:55296
	ds_read_b128 v[194:197], v201 offset:56320
	global_load_lds_dwordx4 v[180:181], off
	v_lshl_add_u64 v[180:181], v[232:233], 0, s[88:89]
	s_mov_b32 m0, s4
	s_nop 0
	global_load_lds_dwordx4 v[180:181], off
	s_setprio 1
	s_barrier
	s_waitcnt lgkmcnt(0)
	s_waitcnt lgkmcnt(0)
	v_mfma_f32_16x16x32_bf16 v[106:109], v[86:89], v[146:149], v[106:109]
	v_mfma_f32_16x16x32_bf16 v[30:33], v[98:101], v[146:149], v[30:33]
	v_mfma_f32_16x16x32_bf16 v[102:105], v[86:89], v[154:157], v[102:105]
	v_mfma_f32_16x16x32_bf16 v[22:25], v[98:101], v[154:157], v[22:25]
	v_mfma_f32_16x16x32_bf16 v[94:97], v[86:89], v[162:165], v[94:97]
	v_mfma_f32_16x16x32_bf16 v[14:17], v[98:101], v[162:165], v[14:17]
	v_mfma_f32_16x16x32_bf16 v[66:69], v[86:89], v[176:179], v[66:69]
	v_mfma_f32_16x16x32_bf16 v[2:5], v[98:101], v[176:179], v[2:5]
	v_mfma_f32_16x16x32_bf16 v[106:109], v[90:93], v[150:153], v[106:109]
	v_mfma_f32_16x16x32_bf16 v[30:33], v[110:113], v[150:153], v[30:33]
	v_mfma_f32_16x16x32_bf16 v[102:105], v[90:93], v[158:161], v[102:105]
	v_mfma_f32_16x16x32_bf16 v[22:25], v[110:113], v[158:161], v[22:25]
	v_mfma_f32_16x16x32_bf16 v[94:97], v[90:93], v[166:169], v[94:97]
	v_mfma_f32_16x16x32_bf16 v[14:17], v[110:113], v[166:169], v[14:17]
	v_mfma_f32_16x16x32_bf16 v[66:69], v[90:93], v[194:197], v[66:69]
	v_mfma_f32_16x16x32_bf16 v[2:5], v[110:113], v[194:197], v[2:5]
	s_setprio 0
	s_barrier
	s_add_u32 s0, s34, 0x40080
	s_addc_u32 s1, s35, 0
	s_mov_b32 m0, s10
	v_lshl_add_u64 v[86:87], s[0:1], 0, v[0:1]
	global_load_lds_dwordx4 v[86:87], off
	v_lshl_add_u64 v[86:87], s[0:1], 0, v[170:171]
	s_mov_b32 m0, s11
	s_nop 0
	global_load_lds_dwordx4 v[86:87], off
	s_waitcnt vmcnt(6)
	s_setprio 1
	s_barrier
	v_mfma_f32_16x16x32_bf16 v[74:77], v[204:207], v[146:149], v[74:77]
	v_mfma_f32_16x16x32_bf16 v[110:113], v[208:211], v[150:153], v[74:77]
	v_mfma_f32_16x16x32_bf16 v[74:77], v[204:207], v[154:157], v[78:81]
	v_mfma_f32_16x16x32_bf16 v[26:29], v[212:215], v[146:149], v[26:29]
	v_mfma_f32_16x16x32_bf16 v[98:101], v[208:211], v[158:161], v[74:77]
	v_mfma_f32_16x16x32_bf16 v[18:21], v[212:215], v[154:157], v[18:21]
	v_mfma_f32_16x16x32_bf16 v[74:77], v[204:207], v[162:165], v[82:85]
	v_mfma_f32_16x16x32_bf16 v[10:13], v[212:215], v[162:165], v[10:13]
	v_mfma_f32_16x16x32_bf16 v[70:73], v[204:207], v[176:179], v[70:73]
	v_mfma_f32_16x16x32_bf16 v[6:9], v[212:215], v[176:179], v[6:9]
	v_mfma_f32_16x16x32_bf16 v[26:29], v[216:219], v[150:153], v[26:29]
	v_mfma_f32_16x16x32_bf16 v[18:21], v[216:219], v[158:161], v[18:21]
	v_mfma_f32_16x16x32_bf16 v[90:93], v[208:211], v[166:169], v[74:77]
	v_mfma_f32_16x16x32_bf16 v[10:13], v[216:219], v[166:169], v[10:13]
	v_mfma_f32_16x16x32_bf16 v[70:73], v[208:211], v[194:197], v[70:73]
	v_mfma_f32_16x16x32_bf16 v[6:9], v[216:219], v[194:197], v[6:9]
	s_setprio 0
	s_add_i32 vcc_lo, vcc_lo, 2
	s_add_u32 s20, s20, 0x100
	s_addc_u32 s21, s21, 0
	s_add_u32 s93, s93, 0x100
	s_addc_u32 s95, s95, 0
	s_cmp_gt_u32 vcc_lo, 13
	s_barrier
	s_cbranch_scc0 .LBB0_705
	s_mov_b32 s100, 0xbfb8aa3b
	v_lshl_or_b32 v180, s48, 7, v185
	v_ashrrev_i32_e32 v181, 31, v180
	v_lshlrev_b64 v[74:75], 2, v[180:181]
	v_lshl_add_u64 v[76:77], s[2:3], 0, v[74:75]
	v_lshl_add_u64 v[86:87], s[76:77], 0, v[74:75]
	v_lshl_add_u64 v[88:89], s[80:81], 0, v[74:75]
	v_lshl_add_u64 v[158:159], s[16:17], 0, v[74:75]
	global_load_dwordx4 v[82:85], v[76:77], off offset:16
	global_load_dwordx4 v[154:157], v[76:77], off
	global_load_dwordx4 v[78:81], v[86:87], off offset:16
	global_load_dwordx4 v[150:153], v[86:87], off
	s_nop 0
	global_load_dwordx4 v[74:77], v[88:89], off offset:16
	global_load_dwordx4 v[146:149], v[88:89], off
	s_nop 0
	global_load_dwordx4 v[86:89], v[158:159], off offset:16
	s_nop 0
	global_load_dwordx4 v[158:161], v[158:159], off
	v_readlane_b32 s0, v254, 24
	s_cmpk_gt_u32 s0, 0xff
	s_cbranch_scc1 .Lup_e0_skip
	s_barrier

.LBB0_780:
	v_add_u32_e32 v30, s15, v202
	ds_read_b128 v[18:21], v30
	ds_read_b128 v[22:25], v30 offset:1024
	ds_read_b128 v[26:29], v30 offset:2048
	ds_read_b128 v[30:33], v30 offset:3072
	s_add_u32 s0, s20, 0xfffc0080
	s_addc_u32 s1, s21, -1
	s_cmp_eq_u32 s28, 12
	s_cselect_b32 s51, s8, s1
	s_cselect_b32 s50, s10, s0
	s_cselect_b32 s35, s11, s26
	s_cselect_b32 s34, s24, s25
	v_lshl_add_u64 v[184:185], s[20:21], 0, v[180:181]
	s_add_i32 m0, s61, 0xc000
	ds_read_b128 v[34:37], v204
	ds_read_b128 v[38:41], v204 offset:1024
	ds_read_b128 v[58:61], v204 offset:2048
	ds_read_b128 v[62:65], v204 offset:3072
	ds_read_b128 v[66:69], v204 offset:4096
	ds_read_b128 v[70:73], v204 offset:5120
	ds_read_b128 v[74:77], v204 offset:6144
	ds_read_b128 v[78:81], v204 offset:7168
	global_load_lds_dwordx4 v[184:185], off
	v_lshl_add_u64 v[184:185], s[20:21], 0, v[182:183]
	s_add_i32 m0, s61, 0xe000
	s_nop 0
	global_load_lds_dwordx4 v[184:185], off
	s_waitcnt lgkmcnt(8)
	s_setprio 1
	s_barrier
	s_waitcnt lgkmcnt(0)
	s_waitcnt lgkmcnt(0)
	v_mfma_f32_16x16x32_bf16 v[174:177], v[18:21], v[34:37], v[174:177]
	v_mfma_f32_16x16x32_bf16 v[170:173], v[26:29], v[34:37], v[170:173]
	v_mfma_f32_16x16x32_bf16 v[158:161], v[18:21], v[58:61], v[158:161]
	v_mfma_f32_16x16x32_bf16 v[154:157], v[26:29], v[58:61], v[154:157]
	v_mfma_f32_16x16x32_bf16 v[142:145], v[18:21], v[66:69], v[142:145]
	v_mfma_f32_16x16x32_bf16 v[138:141], v[26:29], v[66:69], v[138:141]
	v_mfma_f32_16x16x32_bf16 v[126:129], v[18:21], v[74:77], v[126:129]
	v_mfma_f32_16x16x32_bf16 v[122:125], v[26:29], v[74:77], v[122:125]
	v_mfma_f32_16x16x32_bf16 v[174:177], v[22:25], v[38:41], v[174:177]
	v_mfma_f32_16x16x32_bf16 v[170:173], v[30:33], v[38:41], v[170:173]
	v_mfma_f32_16x16x32_bf16 v[158:161], v[22:25], v[62:65], v[158:161]
	v_mfma_f32_16x16x32_bf16 v[154:157], v[30:33], v[62:65], v[154:157]
	v_mfma_f32_16x16x32_bf16 v[142:145], v[22:25], v[70:73], v[142:145]
	v_mfma_f32_16x16x32_bf16 v[138:141], v[30:33], v[70:73], v[138:141]
	v_mfma_f32_16x16x32_bf16 v[126:129], v[22:25], v[78:81], v[126:129]
	v_mfma_f32_16x16x32_bf16 v[122:125], v[30:33], v[78:81], v[122:125]
	s_setprio 0
	s_barrier
	v_add_u32_e32 v188, s63, v202
	s_mov_b32 m0, s55
	ds_read_b128 v[184:187], v188
	ds_read_b128 v[206:209], v188 offset:1024
	ds_read_b128 v[210:213], v188 offset:2048
	ds_read_b128 v[214:217], v188 offset:3072
	v_lshl_add_u64 v[188:189], s[34:35], 0, v[0:1]
	global_load_lds_dwordx4 v[188:189], off
	v_lshl_add_u64 v[222:223], s[34:35], 0, v[178:179]
	s_mov_b32 m0, s60
	s_nop 0
	global_load_lds_dwordx4 v[222:223], off
	s_setprio 1
	s_barrier
	s_waitcnt lgkmcnt(0)
	s_waitcnt lgkmcnt(0)
	v_mfma_f32_16x16x32_bf16 v[166:169], v[184:187], v[34:37], v[166:169]
	v_mfma_f32_16x16x32_bf16 v[34:37], v[210:213], v[34:37], v[162:165]
	v_mfma_f32_16x16x32_bf16 v[166:169], v[206:209], v[38:41], v[166:169]
	v_mfma_f32_16x16x32_bf16 v[34:37], v[214:217], v[38:41], v[34:37]
	v_mfma_f32_16x16x32_bf16 v[38:41], v[184:187], v[58:61], v[150:153]
	v_mfma_f32_16x16x32_bf16 v[58:61], v[210:213], v[58:61], v[146:149]
	v_mfma_f32_16x16x32_bf16 v[38:41], v[206:209], v[62:65], v[38:41]
	v_mfma_f32_16x16x32_bf16 v[58:61], v[214:217], v[62:65], v[58:61]
	v_mfma_f32_16x16x32_bf16 v[62:65], v[184:187], v[66:69], v[134:137]
	v_mfma_f32_16x16x32_bf16 v[66:69], v[210:213], v[66:69], v[130:133]
	v_mfma_f32_16x16x32_bf16 v[62:65], v[206:209], v[70:73], v[62:65]
	v_mfma_f32_16x16x32_bf16 v[66:69], v[214:217], v[70:73], v[66:69]
	v_mfma_f32_16x16x32_bf16 v[70:73], v[184:187], v[74:77], v[118:121]
	v_mfma_f32_16x16x32_bf16 v[74:77], v[210:213], v[74:77], v[114:117]
	v_mfma_f32_16x16x32_bf16 v[70:73], v[206:209], v[78:81], v[70:73]
	v_mfma_f32_16x16x32_bf16 v[74:77], v[214:217], v[78:81], v[74:77]
	s_setprio 0
	s_mov_b32 m0, s61
	v_lshl_add_u64 v[250:251], s[50:51], 0, v[0:1]
	s_barrier
	ds_read_b128 v[78:81], v204 offset:16384
	ds_read_b128 v[114:117], v204 offset:17408
	ds_read_b128 v[118:121], v204 offset:18432
	ds_read_b128 v[130:133], v204 offset:19456
	ds_read_b128 v[134:137], v204 offset:20480
	ds_read_b128 v[146:149], v204 offset:21504
	ds_read_b128 v[150:153], v204 offset:22528
	ds_read_b128 v[162:165], v204 offset:23552
	global_load_lds_dwordx4 v[250:251], off
	v_lshl_add_u64 v[232:233], s[50:51], 0, v[178:179]
	s_mov_b32 m0, s62
	s_nop 0
	global_load_lds_dwordx4 v[232:233], off
	s_setprio 1
	s_barrier
	s_waitcnt lgkmcnt(0)
	s_waitcnt lgkmcnt(0)
	v_mfma_f32_16x16x32_bf16 v[110:113], v[18:21], v[78:81], v[110:113]
	v_mfma_f32_16x16x32_bf16 v[106:109], v[26:29], v[78:81], v[106:109]
	v_mfma_f32_16x16x32_bf16 v[94:97], v[18:21], v[118:121], v[94:97]
	v_mfma_f32_16x16x32_bf16 v[90:93], v[26:29], v[118:121], v[90:93]
	v_mfma_f32_16x16x32_bf16 v[54:57], v[18:21], v[134:137], v[54:57]
	v_mfma_f32_16x16x32_bf16 v[50:53], v[26:29], v[134:137], v[50:53]
	v_mfma_f32_16x16x32_bf16 v[14:17], v[18:21], v[150:153], v[14:17]
	v_mfma_f32_16x16x32_bf16 v[10:13], v[26:29], v[150:153], v[10:13]
	v_mfma_f32_16x16x32_bf16 v[110:113], v[22:25], v[114:117], v[110:113]
	v_mfma_f32_16x16x32_bf16 v[106:109], v[30:33], v[114:117], v[106:109]
	v_mfma_f32_16x16x32_bf16 v[94:97], v[22:25], v[130:133], v[94:97]
	v_mfma_f32_16x16x32_bf16 v[90:93], v[30:33], v[130:133], v[90:93]
	v_mfma_f32_16x16x32_bf16 v[54:57], v[22:25], v[146:149], v[54:57]
	v_mfma_f32_16x16x32_bf16 v[50:53], v[30:33], v[146:149], v[50:53]
	v_mfma_f32_16x16x32_bf16 v[14:17], v[22:25], v[162:165], v[14:17]
	v_mfma_f32_16x16x32_bf16 v[10:13], v[30:33], v[162:165], v[10:13]
	s_setprio 0
	s_barrier
	s_add_u32 s0, s34, 0x40000
	s_addc_u32 s1, s35, 0
	s_mov_b32 m0, s66
	v_lshl_add_u64 v[18:19], s[0:1], 0, v[0:1]
	global_load_lds_dwordx4 v[18:19], off
	v_lshl_add_u64 v[18:19], s[0:1], 0, v[178:179]
	s_mov_b32 m0, s67
	s_nop 0
	global_load_lds_dwordx4 v[18:19], off
	s_waitcnt vmcnt(6)
	s_setprio 1
	s_barrier
	v_mfma_f32_16x16x32_bf16 v[46:49], v[184:187], v[134:137], v[46:49]
	v_mfma_f32_16x16x32_bf16 v[42:45], v[210:213], v[134:137], v[42:45]
	v_mfma_f32_16x16x32_bf16 v[6:9], v[184:187], v[150:153], v[6:9]
	v_mfma_f32_16x16x32_bf16 v[2:5], v[210:213], v[150:153], v[2:5]
	v_mfma_f32_16x16x32_bf16 v[18:21], v[184:187], v[78:81], v[102:105]
	v_mfma_f32_16x16x32_bf16 v[22:25], v[210:213], v[78:81], v[98:101]
	v_mfma_f32_16x16x32_bf16 v[26:29], v[184:187], v[118:121], v[86:89]
	v_mfma_f32_16x16x32_bf16 v[30:33], v[210:213], v[118:121], v[82:85]
	v_mfma_f32_16x16x32_bf16 v[46:49], v[206:209], v[146:149], v[46:49]
	v_mfma_f32_16x16x32_bf16 v[42:45], v[214:217], v[146:149], v[42:45]
	v_mfma_f32_16x16x32_bf16 v[6:9], v[206:209], v[162:165], v[6:9]
	v_mfma_f32_16x16x32_bf16 v[2:5], v[214:217], v[162:165], v[2:5]
	v_mfma_f32_16x16x32_bf16 v[18:21], v[206:209], v[114:117], v[18:21]
	v_mfma_f32_16x16x32_bf16 v[22:25], v[214:217], v[114:117], v[22:25]
	v_mfma_f32_16x16x32_bf16 v[26:29], v[206:209], v[130:133], v[26:29]
	v_mfma_f32_16x16x32_bf16 v[30:33], v[214:217], v[130:133], v[30:33]
	s_setprio 0
	v_add_u32_e32 v98, s72, v202
	s_barrier
	ds_read_b128 v[78:81], v98
	ds_read_b128 v[82:85], v98 offset:1024
	ds_read_b128 v[86:89], v98 offset:2048
	ds_read_b128 v[98:101], v98 offset:3072
	s_add_u32 s0, s50, 0x40000
	s_addc_u32 s1, s51, 0
	s_mov_b32 m0, s68
	v_lshl_add_u64 v[134:135], s[0:1], 0, v[0:1]
	ds_read_b128 v[102:105], v204 offset:32768
	ds_read_b128 v[114:117], v204 offset:33792
	ds_read_b128 v[118:121], v204 offset:34816
	ds_read_b128 v[130:133], v204 offset:35840
	ds_read_b128 v[184:187], v204 offset:36864
	ds_read_b128 v[206:209], v204 offset:37888
	ds_read_b128 v[210:213], v204 offset:38912
	ds_read_b128 v[214:217], v204 offset:39936
	global_load_lds_dwordx4 v[134:135], off
	v_lshl_add_u64 v[134:135], s[0:1], 0, v[178:179]
	s_mov_b32 m0, s69
	s_nop 0
	global_load_lds_dwordx4 v[134:135], off
	s_waitcnt lgkmcnt(8)
	s_setprio 1
	s_barrier
	s_waitcnt lgkmcnt(0)
	s_waitcnt lgkmcnt(0)
	v_mfma_f32_16x16x32_bf16 v[134:137], v[78:81], v[102:105], v[174:177]
	v_mfma_f32_16x16x32_bf16 v[174:177], v[82:85], v[114:117], v[134:137]
	v_mfma_f32_16x16x32_bf16 v[134:137], v[86:89], v[102:105], v[170:173]
	v_mfma_f32_16x16x32_bf16 v[170:173], v[98:101], v[114:117], v[134:137]
	v_mfma_f32_16x16x32_bf16 v[134:137], v[78:81], v[118:121], v[158:161]
	v_mfma_f32_16x16x32_bf16 v[158:161], v[82:85], v[130:133], v[134:137]
	v_mfma_f32_16x16x32_bf16 v[134:137], v[86:89], v[118:121], v[154:157]
	v_mfma_f32_16x16x32_bf16 v[154:157], v[98:101], v[130:133], v[134:137]
	v_mfma_f32_16x16x32_bf16 v[134:137], v[78:81], v[184:187], v[142:145]
	v_mfma_f32_16x16x32_bf16 v[142:145], v[82:85], v[206:209], v[134:137]
	v_mfma_f32_16x16x32_bf16 v[134:137], v[86:89], v[184:187], v[138:141]
	v_mfma_f32_16x16x32_bf16 v[126:129], v[78:81], v[210:213], v[126:129]
	v_mfma_f32_16x16x32_bf16 v[122:125], v[86:89], v[210:213], v[122:125]
	v_mfma_f32_16x16x32_bf16 v[138:141], v[98:101], v[206:209], v[134:137]
	v_mfma_f32_16x16x32_bf16 v[126:129], v[82:85], v[214:217], v[126:129]
	v_mfma_f32_16x16x32_bf16 v[122:125], v[98:101], v[214:217], v[122:125]
	s_setprio 0
	s_barrier
	s_nop 0
	v_add_u32_e32 v134, s77, v202
	s_mov_b32 m0, s73
	ds_read_b128 v[218:221], v134
	ds_read_b128 v[242:245], v134 offset:1024
	ds_read_b128 v[246:249], v134 offset:2048
	ds_read_b128 v[194:197], v134 offset:3072
	v_lshl_add_u64 v[134:135], v[188:189], 0, s[88:89]
	global_load_lds_dwordx4 v[134:135], off
	v_lshl_add_u64 v[134:135], v[222:223], 0, s[88:89]
	s_mov_b32 m0, s74
	s_nop 0
	global_load_lds_dwordx4 v[134:135], off
	s_setprio 1
	s_barrier
	s_waitcnt lgkmcnt(0)
	s_waitcnt lgkmcnt(0)
	v_mfma_f32_16x16x32_bf16 v[34:37], v[246:249], v[102:105], v[34:37]
	v_mfma_f32_16x16x32_bf16 v[162:165], v[194:197], v[114:117], v[34:37]
	v_mfma_f32_16x16x32_bf16 v[34:37], v[218:221], v[118:121], v[38:41]
	v_mfma_f32_16x16x32_bf16 v[150:153], v[242:245], v[130:133], v[34:37]
	v_mfma_f32_16x16x32_bf16 v[34:37], v[246:249], v[118:121], v[58:61]
	v_mfma_f32_16x16x32_bf16 v[134:137], v[218:221], v[102:105], v[166:169]
	v_mfma_f32_16x16x32_bf16 v[146:149], v[194:197], v[130:133], v[34:37]
	v_mfma_f32_16x16x32_bf16 v[34:37], v[218:221], v[184:187], v[62:65]
	v_mfma_f32_16x16x32_bf16 v[166:169], v[242:245], v[114:117], v[134:137]
	v_mfma_f32_16x16x32_bf16 v[134:137], v[242:245], v[206:209], v[34:37]
	v_mfma_f32_16x16x32_bf16 v[34:37], v[246:249], v[184:187], v[66:69]
	v_mfma_f32_16x16x32_bf16 v[130:133], v[194:197], v[206:209], v[34:37]
	v_mfma_f32_16x16x32_bf16 v[34:37], v[218:221], v[210:213], v[70:73]
	v_mfma_f32_16x16x32_bf16 v[118:121], v[242:245], v[214:217], v[34:37]
	v_mfma_f32_16x16x32_bf16 v[34:37], v[246:249], v[210:213], v[74:77]
	v_mfma_f32_16x16x32_bf16 v[114:117], v[194:197], v[214:217], v[34:37]
	s_setprio 0
	s_mov_b32 m0, s75
	v_lshl_add_u64 v[102:103], v[250:251], 0, s[88:89]
	s_barrier
	s_nop 2
	ds_read_b128 v[34:37], v204 offset:49152
	ds_read_b128 v[38:41], v204 offset:50176
	ds_read_b128 v[58:61], v204 offset:51200
	ds_read_b128 v[62:65], v204 offset:52224
	ds_read_b128 v[66:69], v204 offset:53248
	ds_read_b128 v[70:73], v204 offset:54272
	ds_read_b128 v[74:77], v204 offset:55296
	ds_read_b128 v[184:187], v204 offset:56320
	global_load_lds_dwordx4 v[102:103], off
	v_lshl_add_u64 v[102:103], v[232:233], 0, s[88:89]
	s_mov_b32 m0, s76
	s_nop 0
	global_load_lds_dwordx4 v[102:103], off
	s_setprio 1
	s_barrier
	s_waitcnt lgkmcnt(0)
	s_waitcnt lgkmcnt(0)
	v_mfma_f32_16x16x32_bf16 v[102:105], v[78:81], v[34:37], v[110:113]
	v_mfma_f32_16x16x32_bf16 v[110:113], v[82:85], v[38:41], v[102:105]
	v_mfma_f32_16x16x32_bf16 v[102:105], v[86:89], v[34:37], v[106:109]
	v_mfma_f32_16x16x32_bf16 v[94:97], v[78:81], v[58:61], v[94:97]
	v_mfma_f32_16x16x32_bf16 v[90:93], v[86:89], v[58:61], v[90:93]
	v_mfma_f32_16x16x32_bf16 v[54:57], v[78:81], v[66:69], v[54:57]
	v_mfma_f32_16x16x32_bf16 v[50:53], v[86:89], v[66:69], v[50:53]
	v_mfma_f32_16x16x32_bf16 v[14:17], v[78:81], v[74:77], v[14:17]
	v_mfma_f32_16x16x32_bf16 v[10:13], v[86:89], v[74:77], v[10:13]
	v_mfma_f32_16x16x32_bf16 v[106:109], v[98:101], v[38:41], v[102:105]
	v_mfma_f32_16x16x32_bf16 v[94:97], v[82:85], v[62:65], v[94:97]
	v_mfma_f32_16x16x32_bf16 v[90:93], v[98:101], v[62:65], v[90:93]
	v_mfma_f32_16x16x32_bf16 v[54:57], v[82:85], v[70:73], v[54:57]
	v_mfma_f32_16x16x32_bf16 v[50:53], v[98:101], v[70:73], v[50:53]
	v_mfma_f32_16x16x32_bf16 v[14:17], v[82:85], v[184:187], v[14:17]
	v_mfma_f32_16x16x32_bf16 v[10:13], v[98:101], v[184:187], v[10:13]
	s_setprio 0
	s_barrier
	s_add_u32 s0, s34, 0x40080
	s_addc_u32 s1, s35, 0
	s_mov_b32 m0, s78
	v_lshl_add_u64 v[78:79], s[0:1], 0, v[0:1]
	global_load_lds_dwordx4 v[78:79], off
	v_lshl_add_u64 v[78:79], s[0:1], 0, v[178:179]
	s_mov_b32 m0, s79
	s_nop 0
	global_load_lds_dwordx4 v[78:79], off
	s_waitcnt vmcnt(6)
	s_setprio 1
	s_barrier
	v_mfma_f32_16x16x32_bf16 v[18:21], v[218:221], v[34:37], v[18:21]
	v_mfma_f32_16x16x32_bf16 v[102:105], v[242:245], v[38:41], v[18:21]
	v_mfma_f32_16x16x32_bf16 v[18:21], v[246:249], v[34:37], v[22:25]
	v_mfma_f32_16x16x32_bf16 v[98:101], v[194:197], v[38:41], v[18:21]
	v_mfma_f32_16x16x32_bf16 v[18:21], v[218:221], v[58:61], v[26:29]
	v_mfma_f32_16x16x32_bf16 v[86:89], v[242:245], v[62:65], v[18:21]
	v_mfma_f32_16x16x32_bf16 v[18:21], v[246:249], v[58:61], v[30:33]
	v_mfma_f32_16x16x32_bf16 v[82:85], v[194:197], v[62:65], v[18:21]
	v_mfma_f32_16x16x32_bf16 v[18:21], v[218:221], v[66:69], v[46:49]
	v_mfma_f32_16x16x32_bf16 v[46:49], v[242:245], v[70:73], v[18:21]
	v_mfma_f32_16x16x32_bf16 v[18:21], v[246:249], v[66:69], v[42:45]
	v_mfma_f32_16x16x32_bf16 v[6:9], v[218:221], v[74:77], v[6:9]
	v_mfma_f32_16x16x32_bf16 v[2:5], v[246:249], v[74:77], v[2:5]
	v_mfma_f32_16x16x32_bf16 v[42:45], v[194:197], v[70:73], v[18:21]
	v_mfma_f32_16x16x32_bf16 v[6:9], v[242:245], v[184:187], v[6:9]
	v_mfma_f32_16x16x32_bf16 v[2:5], v[194:197], v[184:187], v[2:5]
	s_setprio 0
	s_add_i32 s28, s28, 2
	s_add_u32 s20, s20, 0x100
	s_addc_u32 s21, s21, 0
	s_add_u32 s25, s25, 0x100
	s_addc_u32 s26, s26, 0
	s_cmp_gt_u32 s28, 13
	s_barrier
	s_cbranch_scc0 .LBB0_780
	v_readfirstlane_b32 s98, v191
	s_cmpk_gt_u32 s98, 0xff
	s_cbranch_scc1 .Lrl_e0_780
	s_barrier

.LBB0_794:
	v_add_u32_e32 v0, s10, v161
	ds_read_b128 v[122:125], v0
	ds_read_b128 v[126:129], v0 offset:1024
	ds_read_b128 v[130:133], v0 offset:2048
	ds_read_b128 v[134:137], v0 offset:3072
	s_add_u32 s0, s20, 0xfffc0080
	s_addc_u32 s1, s21, -1
	s_cmp_eq_u32 s71, 12
	s_cselect_b32 s49, s7, s1
	s_cselect_b32 s48, s67, s0
	s_cselect_b32 s35, s3, s70
	s_cselect_b32 s34, s68, s69
	v_lshl_add_u64 v[158:159], s[20:21], 0, v[150:151]
	s_add_i32 m0, s24, 0xc000
	ds_read_b128 v[154:157], v163
	ds_read_b128 v[164:167], v163 offset:1024
	ds_read_b128 v[168:171], v163 offset:2048
	ds_read_b128 v[172:175], v163 offset:3072
	ds_read_b128 v[176:179], v163 offset:4096
	ds_read_b128 v[180:183], v163 offset:5120
	ds_read_b128 v[184:187], v163 offset:6144
	ds_read_b128 v[202:205], v163 offset:7168
	global_load_lds_dwordx4 v[158:159], off
	v_lshl_add_u64 v[158:159], s[20:21], 0, v[152:153]
	s_add_i32 m0, s24, 0xe000
	s_nop 0
	global_load_lds_dwordx4 v[158:159], off
	s_waitcnt lgkmcnt(8)
	s_setprio 1
	s_barrier
	s_waitcnt lgkmcnt(0)
	s_waitcnt lgkmcnt(0)
	v_mfma_f32_16x16x32_bf16 v[142:145], v[122:125], v[154:157], v[142:145]
	v_mfma_f32_16x16x32_bf16 v[138:141], v[130:133], v[154:157], v[138:141]
	v_mfma_f32_16x16x32_bf16 v[110:113], v[122:125], v[168:171], v[110:113]
	v_mfma_f32_16x16x32_bf16 v[106:109], v[130:133], v[168:171], v[106:109]
	v_mfma_f32_16x16x32_bf16 v[94:97], v[122:125], v[176:179], v[94:97]
	v_mfma_f32_16x16x32_bf16 v[90:93], v[130:133], v[176:179], v[90:93]
	v_mfma_f32_16x16x32_bf16 v[78:81], v[122:125], v[184:187], v[78:81]
	v_mfma_f32_16x16x32_bf16 v[74:77], v[130:133], v[184:187], v[74:77]
	v_mfma_f32_16x16x32_bf16 v[142:145], v[126:129], v[164:167], v[142:145]
	v_mfma_f32_16x16x32_bf16 v[138:141], v[134:137], v[164:167], v[138:141]
	v_mfma_f32_16x16x32_bf16 v[110:113], v[126:129], v[172:175], v[110:113]
	v_mfma_f32_16x16x32_bf16 v[106:109], v[134:137], v[172:175], v[106:109]
	v_mfma_f32_16x16x32_bf16 v[94:97], v[126:129], v[180:183], v[94:97]
	v_mfma_f32_16x16x32_bf16 v[90:93], v[134:137], v[180:183], v[90:93]
	v_mfma_f32_16x16x32_bf16 v[78:81], v[126:129], v[202:205], v[78:81]
	v_mfma_f32_16x16x32_bf16 v[74:77], v[134:137], v[202:205], v[74:77]
	s_setprio 0
	s_barrier
	s_mov_b32 m0, s11
	v_add_u32_e32 v0, s26, v161
	v_lshl_add_u64 v[158:159], s[34:35], 0, v[148:149]
	ds_read_b128 v[206:209], v0
	ds_read_b128 v[210:213], v0 offset:1024
	ds_read_b128 v[214:217], v0 offset:2048
	ds_read_b128 v[218:221], v0 offset:3072
	global_load_lds_dwordx4 v[158:159], off
	v_lshl_add_u64 v[188:189], s[34:35], 0, v[146:147]
	s_mov_b32 m0, s19
	s_nop 0
	global_load_lds_dwordx4 v[188:189], off
	s_setprio 1
	s_barrier
	s_waitcnt lgkmcnt(0)
	s_waitcnt lgkmcnt(0)
	v_mfma_f32_16x16x32_bf16 v[118:121], v[206:209], v[154:157], v[118:121]
	v_mfma_f32_16x16x32_bf16 v[114:117], v[214:217], v[154:157], v[114:117]
	v_mfma_f32_16x16x32_bf16 v[102:105], v[206:209], v[168:171], v[102:105]
	v_mfma_f32_16x16x32_bf16 v[98:101], v[214:217], v[168:171], v[98:101]
	v_mfma_f32_16x16x32_bf16 v[86:89], v[206:209], v[176:179], v[86:89]
	v_mfma_f32_16x16x32_bf16 v[82:85], v[214:217], v[176:179], v[82:85]
	v_mfma_f32_16x16x32_bf16 v[70:73], v[206:209], v[184:187], v[70:73]
	v_mfma_f32_16x16x32_bf16 v[66:69], v[214:217], v[184:187], v[66:69]
	v_mfma_f32_16x16x32_bf16 v[118:121], v[210:213], v[164:167], v[118:121]
	v_mfma_f32_16x16x32_bf16 v[114:117], v[218:221], v[164:167], v[114:117]
	v_mfma_f32_16x16x32_bf16 v[102:105], v[210:213], v[172:175], v[102:105]
	v_mfma_f32_16x16x32_bf16 v[98:101], v[218:221], v[172:175], v[98:101]
	v_mfma_f32_16x16x32_bf16 v[86:89], v[210:213], v[180:183], v[86:89]
	v_mfma_f32_16x16x32_bf16 v[82:85], v[218:221], v[180:183], v[82:85]
	v_mfma_f32_16x16x32_bf16 v[70:73], v[210:213], v[202:205], v[70:73]
	v_mfma_f32_16x16x32_bf16 v[66:69], v[218:221], v[202:205], v[66:69]
	s_setprio 0
	s_mov_b32 m0, s24
	v_lshl_add_u64 v[194:195], s[48:49], 0, v[148:149]
	s_barrier
	ds_read_b128 v[154:157], v163 offset:16384
	ds_read_b128 v[164:167], v163 offset:17408
	ds_read_b128 v[168:171], v163 offset:18432
	ds_read_b128 v[172:175], v163 offset:19456
	ds_read_b128 v[176:179], v163 offset:20480
	ds_read_b128 v[180:183], v163 offset:21504
	ds_read_b128 v[184:187], v163 offset:22528
	ds_read_b128 v[202:205], v163 offset:23552
	global_load_lds_dwordx4 v[194:195], off
	v_lshl_add_u64 v[196:197], s[48:49], 0, v[146:147]
	s_mov_b32 m0, s25
	s_nop 0
	global_load_lds_dwordx4 v[196:197], off
	s_setprio 1
	s_barrier
	s_waitcnt lgkmcnt(0)
	s_waitcnt lgkmcnt(0)
	v_mfma_f32_16x16x32_bf16 v[62:65], v[122:125], v[154:157], v[62:65]
	v_mfma_f32_16x16x32_bf16 v[58:61], v[130:133], v[154:157], v[58:61]
	v_mfma_f32_16x16x32_bf16 v[46:49], v[122:125], v[168:171], v[46:49]
	v_mfma_f32_16x16x32_bf16 v[42:45], v[130:133], v[168:171], v[42:45]
	v_mfma_f32_16x16x32_bf16 v[30:33], v[122:125], v[176:179], v[30:33]
	v_mfma_f32_16x16x32_bf16 v[26:29], v[130:133], v[176:179], v[26:29]
	v_mfma_f32_16x16x32_bf16 v[14:17], v[122:125], v[184:187], v[14:17]
	v_mfma_f32_16x16x32_bf16 v[10:13], v[130:133], v[184:187], v[10:13]
	v_mfma_f32_16x16x32_bf16 v[62:65], v[126:129], v[164:167], v[62:65]
	v_mfma_f32_16x16x32_bf16 v[58:61], v[134:137], v[164:167], v[58:61]
	v_mfma_f32_16x16x32_bf16 v[46:49], v[126:129], v[172:175], v[46:49]
	v_mfma_f32_16x16x32_bf16 v[42:45], v[134:137], v[172:175], v[42:45]
	v_mfma_f32_16x16x32_bf16 v[30:33], v[126:129], v[180:183], v[30:33]
	v_mfma_f32_16x16x32_bf16 v[26:29], v[134:137], v[180:183], v[26:29]
	v_mfma_f32_16x16x32_bf16 v[14:17], v[126:129], v[202:205], v[14:17]
	v_mfma_f32_16x16x32_bf16 v[10:13], v[134:137], v[202:205], v[10:13]
	s_setprio 0
	s_barrier
	s_add_u32 s0, s34, 0x40000
	s_addc_u32 s1, s35, 0
	s_mov_b32 m0, s28
	v_lshl_add_u64 v[122:123], s[0:1], 0, v[148:149]
	global_load_lds_dwordx4 v[122:123], off
	v_lshl_add_u64 v[122:123], s[0:1], 0, v[146:147]
	s_mov_b32 m0, s29
	s_nop 0
	global_load_lds_dwordx4 v[122:123], off
	s_waitcnt vmcnt(6)
	s_setprio 1
	s_barrier
	v_mfma_f32_16x16x32_bf16 v[54:57], v[206:209], v[154:157], v[54:57]
	v_mfma_f32_16x16x32_bf16 v[50:53], v[214:217], v[154:157], v[50:53]
	v_mfma_f32_16x16x32_bf16 v[38:41], v[206:209], v[168:171], v[38:41]
	v_mfma_f32_16x16x32_bf16 v[34:37], v[214:217], v[168:171], v[34:37]
	v_mfma_f32_16x16x32_bf16 v[22:25], v[206:209], v[176:179], v[22:25]
	v_mfma_f32_16x16x32_bf16 v[18:21], v[214:217], v[176:179], v[18:21]
	v_mfma_f32_16x16x32_bf16 v[6:9], v[206:209], v[184:187], v[6:9]
	v_mfma_f32_16x16x32_bf16 v[2:5], v[214:217], v[184:187], v[2:5]
	v_mfma_f32_16x16x32_bf16 v[54:57], v[210:213], v[164:167], v[54:57]
	v_mfma_f32_16x16x32_bf16 v[50:53], v[218:221], v[164:167], v[50:53]
	v_mfma_f32_16x16x32_bf16 v[38:41], v[210:213], v[172:175], v[38:41]
	v_mfma_f32_16x16x32_bf16 v[34:37], v[218:221], v[172:175], v[34:37]
	v_mfma_f32_16x16x32_bf16 v[22:25], v[210:213], v[180:183], v[22:25]
	v_mfma_f32_16x16x32_bf16 v[18:21], v[218:221], v[180:183], v[18:21]
	v_mfma_f32_16x16x32_bf16 v[6:9], v[210:213], v[202:205], v[6:9]
	v_mfma_f32_16x16x32_bf16 v[2:5], v[218:221], v[202:205], v[2:5]
	s_setprio 0
	v_add_u32_e32 v0, s43, v161
	s_barrier
	ds_read_b128 v[122:125], v0
	ds_read_b128 v[126:129], v0 offset:1024
	ds_read_b128 v[130:133], v0 offset:2048
	ds_read_b128 v[134:137], v0 offset:3072
	s_add_u32 s0, s48, 0x40000
	s_addc_u32 s1, s49, 0
	s_mov_b32 m0, s30
	v_lshl_add_u64 v[206:207], s[0:1], 0, v[148:149]
	ds_read_b128 v[154:157], v163 offset:32768
	ds_read_b128 v[164:167], v163 offset:33792
	ds_read_b128 v[168:171], v163 offset:34816
	ds_read_b128 v[172:175], v163 offset:35840
	ds_read_b128 v[176:179], v163 offset:36864
	ds_read_b128 v[180:183], v163 offset:37888
	ds_read_b128 v[184:187], v163 offset:38912
	ds_read_b128 v[202:205], v163 offset:39936
	global_load_lds_dwordx4 v[206:207], off
	v_lshl_add_u64 v[206:207], s[0:1], 0, v[146:147]
	s_mov_b32 m0, s36
	s_nop 0
	global_load_lds_dwordx4 v[206:207], off
	s_waitcnt lgkmcnt(8)
	s_setprio 1
	s_barrier
	s_waitcnt lgkmcnt(0)
	s_waitcnt lgkmcnt(0)
	v_mfma_f32_16x16x32_bf16 v[142:145], v[122:125], v[154:157], v[142:145]
	v_mfma_f32_16x16x32_bf16 v[138:141], v[130:133], v[154:157], v[138:141]
	v_mfma_f32_16x16x32_bf16 v[110:113], v[122:125], v[168:171], v[110:113]
	v_mfma_f32_16x16x32_bf16 v[106:109], v[130:133], v[168:171], v[106:109]
	v_mfma_f32_16x16x32_bf16 v[94:97], v[122:125], v[176:179], v[94:97]
	v_mfma_f32_16x16x32_bf16 v[90:93], v[130:133], v[176:179], v[90:93]
	v_mfma_f32_16x16x32_bf16 v[78:81], v[122:125], v[184:187], v[78:81]
	v_mfma_f32_16x16x32_bf16 v[74:77], v[130:133], v[184:187], v[74:77]
	v_mfma_f32_16x16x32_bf16 v[142:145], v[126:129], v[164:167], v[142:145]
	v_mfma_f32_16x16x32_bf16 v[138:141], v[134:137], v[164:167], v[138:141]
	v_mfma_f32_16x16x32_bf16 v[110:113], v[126:129], v[172:175], v[110:113]
	v_mfma_f32_16x16x32_bf16 v[106:109], v[134:137], v[172:175], v[106:109]
	v_mfma_f32_16x16x32_bf16 v[94:97], v[126:129], v[180:183], v[94:97]
	v_mfma_f32_16x16x32_bf16 v[90:93], v[134:137], v[180:183], v[90:93]
	v_mfma_f32_16x16x32_bf16 v[78:81], v[126:129], v[202:205], v[78:81]
	v_mfma_f32_16x16x32_bf16 v[74:77], v[134:137], v[202:205], v[74:77]
	s_setprio 0
	s_barrier
	s_mov_b32 m0, s50
	v_add_u32_e32 v0, s58, v161
	v_lshl_add_u64 v[158:159], v[158:159], 0, s[88:89]
	ds_read_b128 v[206:209], v0
	ds_read_b128 v[210:213], v0 offset:1024
	ds_read_b128 v[214:217], v0 offset:2048
	ds_read_b128 v[218:221], v0 offset:3072
	global_load_lds_dwordx4 v[158:159], off
	v_lshl_add_u64 v[158:159], v[188:189], 0, s[88:89]
	s_mov_b32 m0, s51
	s_nop 0
	global_load_lds_dwordx4 v[158:159], off
	s_setprio 1
	s_barrier
	s_waitcnt lgkmcnt(0)
	s_waitcnt lgkmcnt(0)
	v_mfma_f32_16x16x32_bf16 v[118:121], v[206:209], v[154:157], v[118:121]
	v_mfma_f32_16x16x32_bf16 v[114:117], v[214:217], v[154:157], v[114:117]
	v_mfma_f32_16x16x32_bf16 v[102:105], v[206:209], v[168:171], v[102:105]
	v_mfma_f32_16x16x32_bf16 v[98:101], v[214:217], v[168:171], v[98:101]
	v_mfma_f32_16x16x32_bf16 v[86:89], v[206:209], v[176:179], v[86:89]
	v_mfma_f32_16x16x32_bf16 v[82:85], v[214:217], v[176:179], v[82:85]
	v_mfma_f32_16x16x32_bf16 v[70:73], v[206:209], v[184:187], v[70:73]
	v_mfma_f32_16x16x32_bf16 v[66:69], v[214:217], v[184:187], v[66:69]
	v_mfma_f32_16x16x32_bf16 v[118:121], v[210:213], v[164:167], v[118:121]
	v_mfma_f32_16x16x32_bf16 v[114:117], v[218:221], v[164:167], v[114:117]
	v_mfma_f32_16x16x32_bf16 v[102:105], v[210:213], v[172:175], v[102:105]
	v_mfma_f32_16x16x32_bf16 v[98:101], v[218:221], v[172:175], v[98:101]
	v_mfma_f32_16x16x32_bf16 v[86:89], v[210:213], v[180:183], v[86:89]
	v_mfma_f32_16x16x32_bf16 v[82:85], v[218:221], v[180:183], v[82:85]
	v_mfma_f32_16x16x32_bf16 v[70:73], v[210:213], v[202:205], v[70:73]
	v_mfma_f32_16x16x32_bf16 v[66:69], v[218:221], v[202:205], v[66:69]
	s_setprio 0
	s_mov_b32 m0, s54
	v_lshl_add_u64 v[158:159], v[194:195], 0, s[88:89]
	s_barrier
	ds_read_b128 v[154:157], v163 offset:49152
	ds_read_b128 v[164:167], v163 offset:50176
	ds_read_b128 v[168:171], v163 offset:51200
	ds_read_b128 v[172:175], v163 offset:52224
	ds_read_b128 v[176:179], v163 offset:53248
	ds_read_b128 v[180:183], v163 offset:54272
	ds_read_b128 v[184:187], v163 offset:55296
	ds_read_b128 v[202:205], v163 offset:56320
	global_load_lds_dwordx4 v[158:159], off
	v_lshl_add_u64 v[158:159], v[196:197], 0, s[88:89]
	s_mov_b32 m0, s55
	s_nop 0
	global_load_lds_dwordx4 v[158:159], off
	s_setprio 1
	s_barrier
	s_waitcnt lgkmcnt(0)
	s_waitcnt lgkmcnt(0)
	v_mfma_f32_16x16x32_bf16 v[62:65], v[122:125], v[154:157], v[62:65]
	v_mfma_f32_16x16x32_bf16 v[58:61], v[130:133], v[154:157], v[58:61]
	v_mfma_f32_16x16x32_bf16 v[46:49], v[122:125], v[168:171], v[46:49]
	v_mfma_f32_16x16x32_bf16 v[42:45], v[130:133], v[168:171], v[42:45]
	v_mfma_f32_16x16x32_bf16 v[30:33], v[122:125], v[176:179], v[30:33]
	v_mfma_f32_16x16x32_bf16 v[26:29], v[130:133], v[176:179], v[26:29]
	v_mfma_f32_16x16x32_bf16 v[14:17], v[122:125], v[184:187], v[14:17]
	v_mfma_f32_16x16x32_bf16 v[10:13], v[130:133], v[184:187], v[10:13]
	v_mfma_f32_16x16x32_bf16 v[62:65], v[126:129], v[164:167], v[62:65]
	v_mfma_f32_16x16x32_bf16 v[58:61], v[134:137], v[164:167], v[58:61]
	v_mfma_f32_16x16x32_bf16 v[46:49], v[126:129], v[172:175], v[46:49]
	v_mfma_f32_16x16x32_bf16 v[42:45], v[134:137], v[172:175], v[42:45]
	v_mfma_f32_16x16x32_bf16 v[30:33], v[126:129], v[180:183], v[30:33]
	v_mfma_f32_16x16x32_bf16 v[26:29], v[134:137], v[180:183], v[26:29]
	v_mfma_f32_16x16x32_bf16 v[14:17], v[126:129], v[202:205], v[14:17]
	v_mfma_f32_16x16x32_bf16 v[10:13], v[134:137], v[202:205], v[10:13]
	s_setprio 0
	s_barrier
	s_add_u32 s0, s34, 0x40080
	s_addc_u32 s1, s35, 0
	s_mov_b32 m0, s60
	v_lshl_add_u64 v[122:123], s[0:1], 0, v[148:149]
	global_load_lds_dwordx4 v[122:123], off
	v_lshl_add_u64 v[122:123], s[0:1], 0, v[146:147]
	s_mov_b32 m0, s61
	s_nop 0
	global_load_lds_dwordx4 v[122:123], off
	s_waitcnt vmcnt(6)
	s_setprio 1
	s_barrier
	v_mfma_f32_16x16x32_bf16 v[54:57], v[206:209], v[154:157], v[54:57]
	v_mfma_f32_16x16x32_bf16 v[50:53], v[214:217], v[154:157], v[50:53]
	v_mfma_f32_16x16x32_bf16 v[38:41], v[206:209], v[168:171], v[38:41]
	v_mfma_f32_16x16x32_bf16 v[34:37], v[214:217], v[168:171], v[34:37]
	v_mfma_f32_16x16x32_bf16 v[22:25], v[206:209], v[176:179], v[22:25]
	v_mfma_f32_16x16x32_bf16 v[18:21], v[214:217], v[176:179], v[18:21]
	v_mfma_f32_16x16x32_bf16 v[6:9], v[206:209], v[184:187], v[6:9]
	v_mfma_f32_16x16x32_bf16 v[2:5], v[214:217], v[184:187], v[2:5]
	v_mfma_f32_16x16x32_bf16 v[54:57], v[210:213], v[164:167], v[54:57]
	v_mfma_f32_16x16x32_bf16 v[50:53], v[218:221], v[164:167], v[50:53]
	v_mfma_f32_16x16x32_bf16 v[38:41], v[210:213], v[172:175], v[38:41]
	v_mfma_f32_16x16x32_bf16 v[34:37], v[218:221], v[172:175], v[34:37]
	v_mfma_f32_16x16x32_bf16 v[22:25], v[210:213], v[180:183], v[22:25]
	v_mfma_f32_16x16x32_bf16 v[18:21], v[218:221], v[180:183], v[18:21]
	v_mfma_f32_16x16x32_bf16 v[6:9], v[210:213], v[202:205], v[6:9]
	v_mfma_f32_16x16x32_bf16 v[2:5], v[218:221], v[202:205], v[2:5]
	s_setprio 0
	s_add_i32 s71, s71, 2
	s_add_u32 s20, s20, 0x100
	s_addc_u32 s21, s21, 0
	s_add_u32 s69, s69, 0x100
	s_addc_u32 s70, s70, 0
	s_cmp_gt_u32 s71, 13
	s_barrier
	s_cbranch_scc0 .LBB0_794
	v_readfirstlane_b32 s98, v191
	s_cmpk_gt_u32 s98, 0xff
	s_cbranch_scc1 .Lrl_e0_794
	s_barrier

.LBB0_814:
	v_add_u32_e32 v152, s19, v136
	ds_read_b128 v[138:141], v152
	ds_read_b128 v[142:145], v152 offset:1024
	ds_read_b128 v[148:151], v152 offset:2048
	ds_read_b128 v[162:165], v152 offset:3072
	s_add_i32 s70, s70, 2
	s_cmp_lg_u32 s69, s20
	s_cselect_b32 s1, s20, 0
	s_cselect_b32 s0, s21, 0
	s_add_u32 s34, s16, s1
	s_addc_u32 s35, s17, s0
	s_add_u32 s42, s14, s1
	s_addc_u32 s43, s15, s0
	v_lshl_add_u64 v[152:153], v[134:135], 0, s[20:21]
	v_lshl_add_u64 v[152:153], v[152:153], 0, s[76:77]
	s_add_i32 m0, s52, 0xc000
	ds_read_b128 v[166:169], v137
	ds_read_b128 v[170:173], v137 offset:1024
	ds_read_b128 v[174:177], v137 offset:2048
	ds_read_b128 v[178:181], v137 offset:3072
	ds_read_b128 v[182:185], v137 offset:4096
	ds_read_b128 v[186:189], v137 offset:5120
	ds_read_b128 v[202:205], v137 offset:6144
	ds_read_b128 v[206:209], v137 offset:7168
	global_load_lds_dwordx4 v[152:153], off
	v_lshl_add_u64 v[152:153], v[132:133], 0, s[20:21]
	v_lshl_add_u64 v[152:153], v[152:153], 0, s[76:77]
	s_add_i32 m0, s52, 0xe000
	s_nop 0
	global_load_lds_dwordx4 v[152:153], off
	s_waitcnt lgkmcnt(8)
	s_setprio 1
	s_barrier
	s_waitcnt lgkmcnt(0)
	s_waitcnt lgkmcnt(0)
	v_mfma_f32_16x16x32_bf16 v[126:129], v[138:141], v[166:169], v[126:129]
	v_mfma_f32_16x16x32_bf16 v[122:125], v[148:151], v[166:169], v[122:125]
	v_mfma_f32_16x16x32_bf16 v[118:121], v[138:141], v[174:177], v[118:121]
	v_mfma_f32_16x16x32_bf16 v[114:117], v[148:151], v[174:177], v[114:117]
	v_mfma_f32_16x16x32_bf16 v[110:113], v[138:141], v[182:185], v[110:113]
	v_mfma_f32_16x16x32_bf16 v[106:109], v[148:151], v[182:185], v[106:109]
	v_mfma_f32_16x16x32_bf16 v[102:105], v[138:141], v[202:205], v[102:105]
	v_mfma_f32_16x16x32_bf16 v[98:101], v[148:151], v[202:205], v[98:101]
	v_mfma_f32_16x16x32_bf16 v[126:129], v[142:145], v[170:173], v[126:129]
	v_mfma_f32_16x16x32_bf16 v[122:125], v[162:165], v[170:173], v[122:125]
	v_mfma_f32_16x16x32_bf16 v[118:121], v[142:145], v[178:181], v[118:121]
	v_mfma_f32_16x16x32_bf16 v[114:117], v[162:165], v[178:181], v[114:117]
	v_mfma_f32_16x16x32_bf16 v[110:113], v[142:145], v[186:189], v[110:113]
	v_mfma_f32_16x16x32_bf16 v[106:109], v[162:165], v[186:189], v[106:109]
	v_mfma_f32_16x16x32_bf16 v[102:105], v[142:145], v[206:209], v[102:105]
	v_mfma_f32_16x16x32_bf16 v[98:101], v[162:165], v[206:209], v[98:101]
	s_setprio 0
	s_barrier
	v_add_u32_e32 v152, s24, v136
	s_mov_b32 m0, s50
	ds_read_b128 v[210:213], v152
	ds_read_b128 v[214:217], v152 offset:1024
	ds_read_b128 v[218:221], v152 offset:2048
	ds_read_b128 v[242:245], v152 offset:3072
	v_lshl_add_u64 v[152:153], s[42:43], 0, v[0:1]
	global_load_lds_dwordx4 v[152:153], off
	v_lshl_add_u64 v[194:195], s[42:43], 0, v[130:131]
	s_mov_b32 m0, s51
	s_nop 0
	global_load_lds_dwordx4 v[194:195], off
	s_setprio 1
	s_barrier
	s_waitcnt lgkmcnt(0)
	s_waitcnt lgkmcnt(0)
	v_mfma_f32_16x16x32_bf16 v[94:97], v[210:213], v[166:169], v[94:97]
	v_mfma_f32_16x16x32_bf16 v[90:93], v[218:221], v[166:169], v[90:93]
	v_mfma_f32_16x16x32_bf16 v[86:89], v[210:213], v[174:177], v[86:89]
	v_mfma_f32_16x16x32_bf16 v[82:85], v[218:221], v[174:177], v[82:85]
	v_mfma_f32_16x16x32_bf16 v[78:81], v[210:213], v[182:185], v[78:81]
	v_mfma_f32_16x16x32_bf16 v[74:77], v[218:221], v[182:185], v[74:77]
	v_mfma_f32_16x16x32_bf16 v[70:73], v[210:213], v[202:205], v[70:73]
	v_mfma_f32_16x16x32_bf16 v[66:69], v[218:221], v[202:205], v[66:69]
	v_mfma_f32_16x16x32_bf16 v[94:97], v[214:217], v[170:173], v[94:97]
	v_mfma_f32_16x16x32_bf16 v[90:93], v[242:245], v[170:173], v[90:93]
	v_mfma_f32_16x16x32_bf16 v[86:89], v[214:217], v[178:181], v[86:89]
	v_mfma_f32_16x16x32_bf16 v[82:85], v[242:245], v[178:181], v[82:85]
	v_mfma_f32_16x16x32_bf16 v[78:81], v[214:217], v[186:189], v[78:81]
	v_mfma_f32_16x16x32_bf16 v[74:77], v[242:245], v[186:189], v[74:77]
	v_mfma_f32_16x16x32_bf16 v[70:73], v[214:217], v[206:209], v[70:73]
	v_mfma_f32_16x16x32_bf16 v[66:69], v[242:245], v[206:209], v[66:69]
	s_setprio 0
	s_mov_b32 m0, s52
	v_lshl_add_u64 v[196:197], s[34:35], 0, v[0:1]
	s_barrier
	ds_read_b128 v[166:169], v137 offset:16384
	ds_read_b128 v[170:173], v137 offset:17408
	ds_read_b128 v[174:177], v137 offset:18432
	ds_read_b128 v[178:181], v137 offset:19456
	ds_read_b128 v[182:185], v137 offset:20480
	ds_read_b128 v[186:189], v137 offset:21504
	ds_read_b128 v[202:205], v137 offset:22528
	ds_read_b128 v[206:209], v137 offset:23552
	global_load_lds_dwordx4 v[196:197], off
	v_lshl_add_u64 v[222:223], s[34:35], 0, v[130:131]
	s_mov_b32 m0, s53
	s_nop 0
	global_load_lds_dwordx4 v[222:223], off
	s_setprio 1
	s_barrier
	s_waitcnt lgkmcnt(0)
	s_waitcnt lgkmcnt(0)
	v_mfma_f32_16x16x32_bf16 v[62:65], v[138:141], v[166:169], v[62:65]
	v_mfma_f32_16x16x32_bf16 v[58:61], v[148:151], v[166:169], v[58:61]
	v_mfma_f32_16x16x32_bf16 v[54:57], v[138:141], v[174:177], v[54:57]
	v_mfma_f32_16x16x32_bf16 v[50:53], v[148:151], v[174:177], v[50:53]
	v_mfma_f32_16x16x32_bf16 v[46:49], v[138:141], v[182:185], v[46:49]
	v_mfma_f32_16x16x32_bf16 v[42:45], v[148:151], v[182:185], v[42:45]
	v_mfma_f32_16x16x32_bf16 v[38:41], v[138:141], v[202:205], v[38:41]
	v_mfma_f32_16x16x32_bf16 v[34:37], v[148:151], v[202:205], v[34:37]
	v_mfma_f32_16x16x32_bf16 v[62:65], v[142:145], v[170:173], v[62:65]
	v_mfma_f32_16x16x32_bf16 v[58:61], v[162:165], v[170:173], v[58:61]
	v_mfma_f32_16x16x32_bf16 v[54:57], v[142:145], v[178:181], v[54:57]
	v_mfma_f32_16x16x32_bf16 v[50:53], v[162:165], v[178:181], v[50:53]
	v_mfma_f32_16x16x32_bf16 v[46:49], v[142:145], v[186:189], v[46:49]
	v_mfma_f32_16x16x32_bf16 v[42:45], v[162:165], v[186:189], v[42:45]
	v_mfma_f32_16x16x32_bf16 v[38:41], v[142:145], v[206:209], v[38:41]
	v_mfma_f32_16x16x32_bf16 v[34:37], v[162:165], v[206:209], v[34:37]
	s_setprio 0
	s_barrier
	s_add_u32 s0, s42, s49
	s_addc_u32 s1, s43, 0
	s_mov_b32 m0, s54
	v_lshl_add_u64 v[246:247], s[0:1], 0, v[0:1]
	global_load_lds_dwordx4 v[246:247], off
	v_lshl_add_u64 v[248:249], s[0:1], 0, v[130:131]
	s_mov_b32 m0, s55
	s_nop 0
	global_load_lds_dwordx4 v[248:249], off
	s_waitcnt vmcnt(6)
	s_setprio 1
	s_barrier
	v_mfma_f32_16x16x32_bf16 v[30:33], v[210:213], v[166:169], v[30:33]
	v_mfma_f32_16x16x32_bf16 v[26:29], v[218:221], v[166:169], v[26:29]
	v_mfma_f32_16x16x32_bf16 v[22:25], v[210:213], v[174:177], v[22:25]
	v_mfma_f32_16x16x32_bf16 v[18:21], v[218:221], v[174:177], v[18:21]
	v_mfma_f32_16x16x32_bf16 v[14:17], v[210:213], v[182:185], v[14:17]
	v_mfma_f32_16x16x32_bf16 v[10:13], v[218:221], v[182:185], v[10:13]
	v_mfma_f32_16x16x32_bf16 v[6:9], v[210:213], v[202:205], v[6:9]
	v_mfma_f32_16x16x32_bf16 v[2:5], v[218:221], v[202:205], v[2:5]
	v_mfma_f32_16x16x32_bf16 v[30:33], v[214:217], v[170:173], v[30:33]
	v_mfma_f32_16x16x32_bf16 v[26:29], v[242:245], v[170:173], v[26:29]
	v_mfma_f32_16x16x32_bf16 v[22:25], v[214:217], v[178:181], v[22:25]
	v_mfma_f32_16x16x32_bf16 v[18:21], v[242:245], v[178:181], v[18:21]
	v_mfma_f32_16x16x32_bf16 v[14:17], v[214:217], v[186:189], v[14:17]
	v_mfma_f32_16x16x32_bf16 v[10:13], v[242:245], v[186:189], v[10:13]
	v_mfma_f32_16x16x32_bf16 v[6:9], v[214:217], v[206:209], v[6:9]
	v_mfma_f32_16x16x32_bf16 v[2:5], v[242:245], v[206:209], v[2:5]
	s_setprio 0
	v_add_u32_e32 v162, s25, v136
	s_barrier
	ds_read_b128 v[138:141], v162
	ds_read_b128 v[142:145], v162 offset:1024
	ds_read_b128 v[148:151], v162 offset:2048
	ds_read_b128 v[162:165], v162 offset:3072
	s_add_u32 s0, s34, s49
	s_addc_u32 s1, s35, 0
	s_mov_b32 m0, s58
	v_lshl_add_u64 v[210:211], s[0:1], 0, v[0:1]
	ds_read_b128 v[166:169], v137 offset:32768
	ds_read_b128 v[170:173], v137 offset:33792
	ds_read_b128 v[174:177], v137 offset:34816
	ds_read_b128 v[178:181], v137 offset:35840
	ds_read_b128 v[182:185], v137 offset:36864
	ds_read_b128 v[186:189], v137 offset:37888
	ds_read_b128 v[202:205], v137 offset:38912
	ds_read_b128 v[206:209], v137 offset:39936
	global_load_lds_dwordx4 v[210:211], off
	v_lshl_add_u64 v[210:211], s[0:1], 0, v[130:131]
	s_mov_b32 m0, s60
	s_nop 0
	global_load_lds_dwordx4 v[210:211], off
	s_waitcnt lgkmcnt(8)
	s_setprio 1
	s_barrier
	s_waitcnt lgkmcnt(0)
	s_waitcnt lgkmcnt(0)
	v_mfma_f32_16x16x32_bf16 v[126:129], v[138:141], v[166:169], v[126:129]
	v_mfma_f32_16x16x32_bf16 v[122:125], v[148:151], v[166:169], v[122:125]
	v_mfma_f32_16x16x32_bf16 v[118:121], v[138:141], v[174:177], v[118:121]
	v_mfma_f32_16x16x32_bf16 v[114:117], v[148:151], v[174:177], v[114:117]
	v_mfma_f32_16x16x32_bf16 v[110:113], v[138:141], v[182:185], v[110:113]
	v_mfma_f32_16x16x32_bf16 v[106:109], v[148:151], v[182:185], v[106:109]
	v_mfma_f32_16x16x32_bf16 v[102:105], v[138:141], v[202:205], v[102:105]
	v_mfma_f32_16x16x32_bf16 v[98:101], v[148:151], v[202:205], v[98:101]
	v_mfma_f32_16x16x32_bf16 v[126:129], v[142:145], v[170:173], v[126:129]
	v_mfma_f32_16x16x32_bf16 v[122:125], v[162:165], v[170:173], v[122:125]
	v_mfma_f32_16x16x32_bf16 v[118:121], v[142:145], v[178:181], v[118:121]
	v_mfma_f32_16x16x32_bf16 v[114:117], v[162:165], v[178:181], v[114:117]
	v_mfma_f32_16x16x32_bf16 v[110:113], v[142:145], v[186:189], v[110:113]
	v_mfma_f32_16x16x32_bf16 v[106:109], v[162:165], v[186:189], v[106:109]
	v_mfma_f32_16x16x32_bf16 v[102:105], v[142:145], v[206:209], v[102:105]
	v_mfma_f32_16x16x32_bf16 v[98:101], v[162:165], v[206:209], v[98:101]
	s_setprio 0
	s_barrier
	s_mov_b32 m0, s61
	v_add_u32_e32 v201, s26, v136
	v_lshl_add_u64 v[152:153], v[152:153], 0, s[88:89]
	ds_read_b128 v[210:213], v201
	ds_read_b128 v[214:217], v201 offset:1024
	ds_read_b128 v[218:221], v201 offset:2048
	ds_read_b128 v[242:245], v201 offset:3072
	global_load_lds_dwordx4 v[152:153], off
	v_lshl_add_u64 v[152:153], v[194:195], 0, s[88:89]
	s_mov_b32 m0, s62
	s_nop 0
	global_load_lds_dwordx4 v[152:153], off
	s_setprio 1
	s_barrier
	s_waitcnt lgkmcnt(0)
	s_waitcnt lgkmcnt(0)
	v_mfma_f32_16x16x32_bf16 v[94:97], v[210:213], v[166:169], v[94:97]
	v_mfma_f32_16x16x32_bf16 v[90:93], v[218:221], v[166:169], v[90:93]
	v_mfma_f32_16x16x32_bf16 v[86:89], v[210:213], v[174:177], v[86:89]
	v_mfma_f32_16x16x32_bf16 v[82:85], v[218:221], v[174:177], v[82:85]
	v_mfma_f32_16x16x32_bf16 v[78:81], v[210:213], v[182:185], v[78:81]
	v_mfma_f32_16x16x32_bf16 v[74:77], v[218:221], v[182:185], v[74:77]
	v_mfma_f32_16x16x32_bf16 v[70:73], v[210:213], v[202:205], v[70:73]
	v_mfma_f32_16x16x32_bf16 v[66:69], v[218:221], v[202:205], v[66:69]
	v_mfma_f32_16x16x32_bf16 v[94:97], v[214:217], v[170:173], v[94:97]
	v_mfma_f32_16x16x32_bf16 v[90:93], v[242:245], v[170:173], v[90:93]
	v_mfma_f32_16x16x32_bf16 v[86:89], v[214:217], v[178:181], v[86:89]
	v_mfma_f32_16x16x32_bf16 v[82:85], v[242:245], v[178:181], v[82:85]
	v_mfma_f32_16x16x32_bf16 v[78:81], v[214:217], v[186:189], v[78:81]
	v_mfma_f32_16x16x32_bf16 v[74:77], v[242:245], v[186:189], v[74:77]
	v_mfma_f32_16x16x32_bf16 v[70:73], v[214:217], v[206:209], v[70:73]
	v_mfma_f32_16x16x32_bf16 v[66:69], v[242:245], v[206:209], v[66:69]
	s_setprio 0
	s_mov_b32 m0, s63
	v_lshl_add_u64 v[152:153], v[196:197], 0, s[88:89]
	s_barrier
	ds_read_b128 v[166:169], v137 offset:49152
	ds_read_b128 v[170:173], v137 offset:50176
	ds_read_b128 v[174:177], v137 offset:51200
	ds_read_b128 v[178:181], v137 offset:52224
	ds_read_b128 v[182:185], v137 offset:53248
	ds_read_b128 v[186:189], v137 offset:54272
	ds_read_b128 v[202:205], v137 offset:55296
	ds_read_b128 v[206:209], v137 offset:56320
	global_load_lds_dwordx4 v[152:153], off
	v_lshl_add_u64 v[152:153], v[222:223], 0, s[88:89]
	s_mov_b32 m0, s66
	s_nop 0
	global_load_lds_dwordx4 v[152:153], off
	s_setprio 1
	s_barrier
	s_waitcnt lgkmcnt(0)
	s_waitcnt lgkmcnt(0)
	v_mfma_f32_16x16x32_bf16 v[62:65], v[138:141], v[166:169], v[62:65]
	v_mfma_f32_16x16x32_bf16 v[58:61], v[148:151], v[166:169], v[58:61]
	v_mfma_f32_16x16x32_bf16 v[54:57], v[138:141], v[174:177], v[54:57]
	v_mfma_f32_16x16x32_bf16 v[50:53], v[148:151], v[174:177], v[50:53]
	v_mfma_f32_16x16x32_bf16 v[46:49], v[138:141], v[182:185], v[46:49]
	v_mfma_f32_16x16x32_bf16 v[42:45], v[148:151], v[182:185], v[42:45]
	v_mfma_f32_16x16x32_bf16 v[38:41], v[138:141], v[202:205], v[38:41]
	v_mfma_f32_16x16x32_bf16 v[34:37], v[148:151], v[202:205], v[34:37]
	v_mfma_f32_16x16x32_bf16 v[62:65], v[142:145], v[170:173], v[62:65]
	v_mfma_f32_16x16x32_bf16 v[58:61], v[162:165], v[170:173], v[58:61]
	v_mfma_f32_16x16x32_bf16 v[54:57], v[142:145], v[178:181], v[54:57]
	v_mfma_f32_16x16x32_bf16 v[50:53], v[162:165], v[178:181], v[50:53]
	v_mfma_f32_16x16x32_bf16 v[46:49], v[142:145], v[186:189], v[46:49]
	v_mfma_f32_16x16x32_bf16 v[42:45], v[162:165], v[186:189], v[42:45]
	v_mfma_f32_16x16x32_bf16 v[38:41], v[142:145], v[206:209], v[38:41]
	v_mfma_f32_16x16x32_bf16 v[34:37], v[162:165], v[206:209], v[34:37]
	s_setprio 0
	s_barrier
	s_mov_b32 m0, s67
	v_lshl_add_u64 v[138:139], v[246:247], 0, s[88:89]
	global_load_lds_dwordx4 v[138:139], off
	v_lshl_add_u64 v[138:139], v[248:249], 0, s[88:89]
	s_mov_b32 m0, s68
	s_nop 0
	global_load_lds_dwordx4 v[138:139], off
	s_waitcnt vmcnt(6)
	s_setprio 1
	s_barrier
	v_mfma_f32_16x16x32_bf16 v[30:33], v[210:213], v[166:169], v[30:33]
	v_mfma_f32_16x16x32_bf16 v[26:29], v[218:221], v[166:169], v[26:29]
	v_mfma_f32_16x16x32_bf16 v[22:25], v[210:213], v[174:177], v[22:25]
	v_mfma_f32_16x16x32_bf16 v[18:21], v[218:221], v[174:177], v[18:21]
	v_mfma_f32_16x16x32_bf16 v[14:17], v[210:213], v[182:185], v[14:17]
	v_mfma_f32_16x16x32_bf16 v[10:13], v[218:221], v[182:185], v[10:13]
	v_mfma_f32_16x16x32_bf16 v[6:9], v[210:213], v[202:205], v[6:9]
	v_mfma_f32_16x16x32_bf16 v[2:5], v[218:221], v[202:205], v[2:5]
	v_mfma_f32_16x16x32_bf16 v[30:33], v[214:217], v[170:173], v[30:33]
	v_mfma_f32_16x16x32_bf16 v[26:29], v[242:245], v[170:173], v[26:29]
	v_mfma_f32_16x16x32_bf16 v[22:25], v[214:217], v[178:181], v[22:25]
	v_mfma_f32_16x16x32_bf16 v[18:21], v[242:245], v[178:181], v[18:21]
	v_mfma_f32_16x16x32_bf16 v[14:17], v[214:217], v[186:189], v[14:17]
	v_mfma_f32_16x16x32_bf16 v[10:13], v[242:245], v[186:189], v[10:13]
	v_mfma_f32_16x16x32_bf16 v[6:9], v[214:217], v[206:209], v[6:9]
	v_mfma_f32_16x16x32_bf16 v[2:5], v[242:245], v[206:209], v[2:5]
	s_setprio 0
	s_add_u32 s20, s20, 0x100
	s_addc_u32 s21, s21, 0
	s_cmp_ge_u32 s70, s44
	s_barrier
	s_cbranch_scc0 .LBB0_814
	v_readfirstlane_b32 s98, v191
	s_cmpk_gt_u32 s98, 0xff
	s_cbranch_scc1 .Lrl_e0_814
	s_barrier

.LBB0_1241:
	v_add_u32_e32 v0, s37, v144
	ds_read_b128 v[140:143], v0
	ds_read_b128 v[150:153], v0 offset:1024
	ds_read_b128 v[154:157], v0 offset:2048
	ds_read_b128 v[158:161], v0 offset:3072
	s_add_u32 s0, s20, 0xfffc0080
	s_addc_u32 s1, s21, -1
	s_cmp_eq_u32 s51, 12
	s_cselect_b32 s49, s15, s1
	s_cselect_b32 s48, s29, s0
	s_cselect_b32 s35, s7, s50
	s_cselect_b32 s34, s43, s45
	v_lshl_add_u64 v[194:195], s[20:21], 0, v[136:137]
	s_add_i32 m0, s66, 0xc000
	ds_read_b128 v[162:165], v149
	ds_read_b128 v[166:169], v149 offset:1024
	ds_read_b128 v[170:173], v149 offset:2048
	ds_read_b128 v[174:177], v149 offset:3072
	ds_read_b128 v[178:181], v149 offset:4096
	ds_read_b128 v[182:185], v149 offset:5120
	ds_read_b128 v[186:189], v149 offset:6144
	ds_read_b128 v[202:205], v149 offset:7168
	global_load_lds_dwordx4 v[194:195], off
	v_lshl_add_u64 v[194:195], s[20:21], 0, v[138:139]
	s_add_i32 m0, s66, 0xe000
	s_nop 0
	global_load_lds_dwordx4 v[194:195], off
	s_waitcnt lgkmcnt(8)
	s_setprio 1
	s_barrier
	s_waitcnt lgkmcnt(0)
	s_waitcnt lgkmcnt(0)
	v_mfma_f32_16x16x32_bf16 v[126:129], v[140:143], v[162:165], v[126:129]
	v_mfma_f32_16x16x32_bf16 v[122:125], v[154:157], v[162:165], v[122:125]
	v_mfma_f32_16x16x32_bf16 v[110:113], v[140:143], v[170:173], v[110:113]
	v_mfma_f32_16x16x32_bf16 v[106:109], v[154:157], v[170:173], v[106:109]
	v_mfma_f32_16x16x32_bf16 v[94:97], v[140:143], v[178:181], v[94:97]
	v_mfma_f32_16x16x32_bf16 v[90:93], v[154:157], v[178:181], v[90:93]
	v_mfma_f32_16x16x32_bf16 v[78:81], v[140:143], v[186:189], v[78:81]
	v_mfma_f32_16x16x32_bf16 v[74:77], v[154:157], v[186:189], v[74:77]
	v_mfma_f32_16x16x32_bf16 v[126:129], v[150:153], v[166:169], v[126:129]
	v_mfma_f32_16x16x32_bf16 v[122:125], v[158:161], v[166:169], v[122:125]
	v_mfma_f32_16x16x32_bf16 v[110:113], v[150:153], v[174:177], v[110:113]
	v_mfma_f32_16x16x32_bf16 v[106:109], v[158:161], v[174:177], v[106:109]
	v_mfma_f32_16x16x32_bf16 v[94:97], v[150:153], v[182:185], v[94:97]
	v_mfma_f32_16x16x32_bf16 v[90:93], v[158:161], v[182:185], v[90:93]
	v_mfma_f32_16x16x32_bf16 v[78:81], v[150:153], v[202:205], v[78:81]
	v_mfma_f32_16x16x32_bf16 v[74:77], v[158:161], v[202:205], v[74:77]
	s_setprio 0
	s_barrier
	s_mov_b32 m0, s62
	v_add_u32_e32 v0, s26, v144
	v_lshl_add_u64 v[194:195], s[34:35], 0, v[130:131]
	ds_read_b128 v[206:209], v0
	ds_read_b128 v[210:213], v0 offset:1024
	ds_read_b128 v[214:217], v0 offset:2048
	ds_read_b128 v[218:221], v0 offset:3072
	global_load_lds_dwordx4 v[194:195], off
	v_lshl_add_u64 v[196:197], s[34:35], 0, v[132:133]
	s_mov_b32 m0, s63
	s_nop 0
	global_load_lds_dwordx4 v[196:197], off
	s_setprio 1
	s_barrier
	s_waitcnt lgkmcnt(0)
	s_waitcnt lgkmcnt(0)
	v_mfma_f32_16x16x32_bf16 v[118:121], v[206:209], v[162:165], v[118:121]
	v_mfma_f32_16x16x32_bf16 v[114:117], v[214:217], v[162:165], v[114:117]
	v_mfma_f32_16x16x32_bf16 v[102:105], v[206:209], v[170:173], v[102:105]
	v_mfma_f32_16x16x32_bf16 v[98:101], v[214:217], v[170:173], v[98:101]
	v_mfma_f32_16x16x32_bf16 v[86:89], v[206:209], v[178:181], v[86:89]
	v_mfma_f32_16x16x32_bf16 v[82:85], v[214:217], v[178:181], v[82:85]
	v_mfma_f32_16x16x32_bf16 v[70:73], v[206:209], v[186:189], v[70:73]
	v_mfma_f32_16x16x32_bf16 v[66:69], v[214:217], v[186:189], v[66:69]
	v_mfma_f32_16x16x32_bf16 v[118:121], v[210:213], v[166:169], v[118:121]
	v_mfma_f32_16x16x32_bf16 v[114:117], v[218:221], v[166:169], v[114:117]
	v_mfma_f32_16x16x32_bf16 v[102:105], v[210:213], v[174:177], v[102:105]
	v_mfma_f32_16x16x32_bf16 v[98:101], v[218:221], v[174:177], v[98:101]
	v_mfma_f32_16x16x32_bf16 v[86:89], v[210:213], v[182:185], v[86:89]
	v_mfma_f32_16x16x32_bf16 v[82:85], v[218:221], v[182:185], v[82:85]
	v_mfma_f32_16x16x32_bf16 v[70:73], v[210:213], v[202:205], v[70:73]
	v_mfma_f32_16x16x32_bf16 v[66:69], v[218:221], v[202:205], v[66:69]
	s_setprio 0
	s_mov_b32 m0, s66
	v_lshl_add_u64 v[222:223], s[48:49], 0, v[130:131]
	s_barrier
	ds_read_b128 v[162:165], v149 offset:16384
	ds_read_b128 v[166:169], v149 offset:17408
	ds_read_b128 v[170:173], v149 offset:18432
	ds_read_b128 v[174:177], v149 offset:19456
	ds_read_b128 v[178:181], v149 offset:20480
	ds_read_b128 v[182:185], v149 offset:21504
	ds_read_b128 v[186:189], v149 offset:22528
	ds_read_b128 v[202:205], v149 offset:23552
	global_load_lds_dwordx4 v[222:223], off
	v_lshl_add_u64 v[242:243], s[48:49], 0, v[132:133]
	s_mov_b32 m0, s67
	s_nop 0
	global_load_lds_dwordx4 v[242:243], off
	s_setprio 1
	s_barrier
	s_waitcnt lgkmcnt(0)
	s_waitcnt lgkmcnt(0)
	v_mfma_f32_16x16x32_bf16 v[62:65], v[140:143], v[162:165], v[62:65]
	v_mfma_f32_16x16x32_bf16 v[58:61], v[154:157], v[162:165], v[58:61]
	v_mfma_f32_16x16x32_bf16 v[46:49], v[140:143], v[170:173], v[46:49]
	v_mfma_f32_16x16x32_bf16 v[42:45], v[154:157], v[170:173], v[42:45]
	v_mfma_f32_16x16x32_bf16 v[30:33], v[140:143], v[178:181], v[30:33]
	v_mfma_f32_16x16x32_bf16 v[26:29], v[154:157], v[178:181], v[26:29]
	v_mfma_f32_16x16x32_bf16 v[14:17], v[140:143], v[186:189], v[14:17]
	v_mfma_f32_16x16x32_bf16 v[10:13], v[154:157], v[186:189], v[10:13]
	v_mfma_f32_16x16x32_bf16 v[62:65], v[150:153], v[166:169], v[62:65]
	v_mfma_f32_16x16x32_bf16 v[58:61], v[158:161], v[166:169], v[58:61]
	v_mfma_f32_16x16x32_bf16 v[46:49], v[150:153], v[174:177], v[46:49]
	v_mfma_f32_16x16x32_bf16 v[42:45], v[158:161], v[174:177], v[42:45]
	v_mfma_f32_16x16x32_bf16 v[30:33], v[150:153], v[182:185], v[30:33]
	v_mfma_f32_16x16x32_bf16 v[26:29], v[158:161], v[182:185], v[26:29]
	v_mfma_f32_16x16x32_bf16 v[14:17], v[150:153], v[202:205], v[14:17]
	v_mfma_f32_16x16x32_bf16 v[10:13], v[158:161], v[202:205], v[10:13]
	s_setprio 0
	s_barrier
	s_add_u32 s0, s34, 0x40000
	s_addc_u32 s1, s35, 0
	s_mov_b32 m0, s68
	v_lshl_add_u64 v[140:141], s[0:1], 0, v[130:131]
	global_load_lds_dwordx4 v[140:141], off
	v_lshl_add_u64 v[140:141], s[0:1], 0, v[132:133]
	s_mov_b32 m0, s28
	s_nop 0
	global_load_lds_dwordx4 v[140:141], off
	s_waitcnt vmcnt(6)
	s_setprio 1
	s_barrier
	v_mfma_f32_16x16x32_bf16 v[54:57], v[206:209], v[162:165], v[54:57]
	v_mfma_f32_16x16x32_bf16 v[50:53], v[214:217], v[162:165], v[50:53]
	v_mfma_f32_16x16x32_bf16 v[38:41], v[206:209], v[170:173], v[38:41]
	v_mfma_f32_16x16x32_bf16 v[34:37], v[214:217], v[170:173], v[34:37]
	v_mfma_f32_16x16x32_bf16 v[22:25], v[206:209], v[178:181], v[22:25]
	v_mfma_f32_16x16x32_bf16 v[18:21], v[214:217], v[178:181], v[18:21]
	v_mfma_f32_16x16x32_bf16 v[6:9], v[206:209], v[186:189], v[6:9]
	v_mfma_f32_16x16x32_bf16 v[2:5], v[214:217], v[186:189], v[2:5]
	v_mfma_f32_16x16x32_bf16 v[54:57], v[210:213], v[166:169], v[54:57]
	v_mfma_f32_16x16x32_bf16 v[50:53], v[218:221], v[166:169], v[50:53]
	v_mfma_f32_16x16x32_bf16 v[38:41], v[210:213], v[174:177], v[38:41]
	v_mfma_f32_16x16x32_bf16 v[34:37], v[218:221], v[174:177], v[34:37]
	v_mfma_f32_16x16x32_bf16 v[22:25], v[210:213], v[182:185], v[22:25]
	v_mfma_f32_16x16x32_bf16 v[18:21], v[218:221], v[182:185], v[18:21]
	v_mfma_f32_16x16x32_bf16 v[6:9], v[210:213], v[202:205], v[6:9]
	v_mfma_f32_16x16x32_bf16 v[2:5], v[218:221], v[202:205], v[2:5]
	s_setprio 0
	v_add_u32_e32 v0, s36, v144
	s_barrier
	ds_read_b128 v[140:143], v0
	ds_read_b128 v[150:153], v0 offset:1024
	ds_read_b128 v[154:157], v0 offset:2048
	ds_read_b128 v[158:161], v0 offset:3072
	s_add_u32 s0, s48, 0x40000
	s_addc_u32 s1, s49, 0
	s_mov_b32 m0, s30
	v_lshl_add_u64 v[206:207], s[0:1], 0, v[130:131]
	ds_read_b128 v[162:165], v149 offset:32768
	ds_read_b128 v[166:169], v149 offset:33792
	ds_read_b128 v[170:173], v149 offset:34816
	ds_read_b128 v[174:177], v149 offset:35840
	ds_read_b128 v[178:181], v149 offset:36864
	ds_read_b128 v[182:185], v149 offset:37888
	ds_read_b128 v[186:189], v149 offset:38912
	ds_read_b128 v[202:205], v149 offset:39936
	global_load_lds_dwordx4 v[206:207], off
	v_lshl_add_u64 v[206:207], s[0:1], 0, v[132:133]
	s_mov_b32 m0, s69
	s_nop 0
	global_load_lds_dwordx4 v[206:207], off
	s_waitcnt lgkmcnt(8)
	s_setprio 1
	s_barrier
	s_waitcnt lgkmcnt(0)
	s_waitcnt lgkmcnt(0)
	v_mfma_f32_16x16x32_bf16 v[126:129], v[140:143], v[162:165], v[126:129]
	v_mfma_f32_16x16x32_bf16 v[122:125], v[154:157], v[162:165], v[122:125]
	v_mfma_f32_16x16x32_bf16 v[110:113], v[140:143], v[170:173], v[110:113]
	v_mfma_f32_16x16x32_bf16 v[106:109], v[154:157], v[170:173], v[106:109]
	v_mfma_f32_16x16x32_bf16 v[94:97], v[140:143], v[178:181], v[94:97]
	v_mfma_f32_16x16x32_bf16 v[90:93], v[154:157], v[178:181], v[90:93]
	v_mfma_f32_16x16x32_bf16 v[78:81], v[140:143], v[186:189], v[78:81]
	v_mfma_f32_16x16x32_bf16 v[74:77], v[154:157], v[186:189], v[74:77]
	v_mfma_f32_16x16x32_bf16 v[126:129], v[150:153], v[166:169], v[126:129]
	v_mfma_f32_16x16x32_bf16 v[122:125], v[158:161], v[166:169], v[122:125]
	v_mfma_f32_16x16x32_bf16 v[110:113], v[150:153], v[174:177], v[110:113]
	v_mfma_f32_16x16x32_bf16 v[106:109], v[158:161], v[174:177], v[106:109]
	v_mfma_f32_16x16x32_bf16 v[94:97], v[150:153], v[182:185], v[94:97]
	v_mfma_f32_16x16x32_bf16 v[90:93], v[158:161], v[182:185], v[90:93]
	v_mfma_f32_16x16x32_bf16 v[78:81], v[150:153], v[202:205], v[78:81]
	v_mfma_f32_16x16x32_bf16 v[74:77], v[158:161], v[202:205], v[74:77]
	s_setprio 0
	s_barrier
	s_mov_b32 m0, s38
	v_add_u32_e32 v0, s8, v144
	v_lshl_add_u64 v[194:195], v[194:195], 0, s[88:89]
	ds_read_b128 v[206:209], v0
	ds_read_b128 v[210:213], v0 offset:1024
	ds_read_b128 v[214:217], v0 offset:2048
	ds_read_b128 v[218:221], v0 offset:3072
	global_load_lds_dwordx4 v[194:195], off
	v_lshl_add_u64 v[194:195], v[196:197], 0, s[88:89]
	s_mov_b32 m0, s58
	s_nop 0
	global_load_lds_dwordx4 v[194:195], off
	s_setprio 1
	s_barrier
	s_waitcnt lgkmcnt(0)
	s_waitcnt lgkmcnt(0)
	v_mfma_f32_16x16x32_bf16 v[118:121], v[206:209], v[162:165], v[118:121]
	v_mfma_f32_16x16x32_bf16 v[114:117], v[214:217], v[162:165], v[114:117]
	v_mfma_f32_16x16x32_bf16 v[102:105], v[206:209], v[170:173], v[102:105]
	v_mfma_f32_16x16x32_bf16 v[98:101], v[214:217], v[170:173], v[98:101]
	v_mfma_f32_16x16x32_bf16 v[86:89], v[206:209], v[178:181], v[86:89]
	v_mfma_f32_16x16x32_bf16 v[82:85], v[214:217], v[178:181], v[82:85]
	v_mfma_f32_16x16x32_bf16 v[70:73], v[206:209], v[186:189], v[70:73]
	v_mfma_f32_16x16x32_bf16 v[66:69], v[214:217], v[186:189], v[66:69]
	v_mfma_f32_16x16x32_bf16 v[118:121], v[210:213], v[166:169], v[118:121]
	v_mfma_f32_16x16x32_bf16 v[114:117], v[218:221], v[166:169], v[114:117]
	v_mfma_f32_16x16x32_bf16 v[102:105], v[210:213], v[174:177], v[102:105]
	v_mfma_f32_16x16x32_bf16 v[98:101], v[218:221], v[174:177], v[98:101]
	v_mfma_f32_16x16x32_bf16 v[86:89], v[210:213], v[182:185], v[86:89]
	v_mfma_f32_16x16x32_bf16 v[82:85], v[218:221], v[182:185], v[82:85]
	v_mfma_f32_16x16x32_bf16 v[70:73], v[210:213], v[202:205], v[70:73]
	v_mfma_f32_16x16x32_bf16 v[66:69], v[218:221], v[202:205], v[66:69]
	s_setprio 0
	s_mov_b32 m0, s76
	v_lshl_add_u64 v[194:195], v[222:223], 0, s[88:89]
	s_barrier
	ds_read_b128 v[162:165], v149 offset:49152
	ds_read_b128 v[166:169], v149 offset:50176
	ds_read_b128 v[170:173], v149 offset:51200
	ds_read_b128 v[174:177], v149 offset:52224
	ds_read_b128 v[178:181], v149 offset:53248
	ds_read_b128 v[182:185], v149 offset:54272
	ds_read_b128 v[186:189], v149 offset:55296
	ds_read_b128 v[202:205], v149 offset:56320
	global_load_lds_dwordx4 v[194:195], off
	v_lshl_add_u64 v[194:195], v[242:243], 0, s[88:89]
	s_mov_b32 m0, s4
	s_nop 0
	global_load_lds_dwordx4 v[194:195], off
	s_setprio 1
	s_barrier
	s_waitcnt lgkmcnt(0)
	s_waitcnt lgkmcnt(0)
	v_mfma_f32_16x16x32_bf16 v[62:65], v[140:143], v[162:165], v[62:65]
	v_mfma_f32_16x16x32_bf16 v[58:61], v[154:157], v[162:165], v[58:61]
	v_mfma_f32_16x16x32_bf16 v[46:49], v[140:143], v[170:173], v[46:49]
	v_mfma_f32_16x16x32_bf16 v[42:45], v[154:157], v[170:173], v[42:45]
	v_mfma_f32_16x16x32_bf16 v[30:33], v[140:143], v[178:181], v[30:33]
	v_mfma_f32_16x16x32_bf16 v[26:29], v[154:157], v[178:181], v[26:29]
	v_mfma_f32_16x16x32_bf16 v[14:17], v[140:143], v[186:189], v[14:17]
	v_mfma_f32_16x16x32_bf16 v[10:13], v[154:157], v[186:189], v[10:13]
	v_mfma_f32_16x16x32_bf16 v[62:65], v[150:153], v[166:169], v[62:65]
	v_mfma_f32_16x16x32_bf16 v[58:61], v[158:161], v[166:169], v[58:61]
	v_mfma_f32_16x16x32_bf16 v[46:49], v[150:153], v[174:177], v[46:49]
	v_mfma_f32_16x16x32_bf16 v[42:45], v[158:161], v[174:177], v[42:45]
	v_mfma_f32_16x16x32_bf16 v[30:33], v[150:153], v[182:185], v[30:33]
	v_mfma_f32_16x16x32_bf16 v[26:29], v[158:161], v[182:185], v[26:29]
	v_mfma_f32_16x16x32_bf16 v[14:17], v[150:153], v[202:205], v[14:17]
	v_mfma_f32_16x16x32_bf16 v[10:13], v[158:161], v[202:205], v[10:13]
	s_setprio 0
	s_barrier
	s_add_u32 s0, s34, 0x40080
	s_addc_u32 s1, s35, 0
	s_mov_b32 m0, s10
	v_lshl_add_u64 v[140:141], s[0:1], 0, v[130:131]
	global_load_lds_dwordx4 v[140:141], off
	v_lshl_add_u64 v[140:141], s[0:1], 0, v[132:133]
	s_mov_b32 m0, s11
	s_nop 0
	global_load_lds_dwordx4 v[140:141], off
	s_waitcnt vmcnt(6)
	s_setprio 1
	s_barrier
	v_mfma_f32_16x16x32_bf16 v[54:57], v[206:209], v[162:165], v[54:57]
	v_mfma_f32_16x16x32_bf16 v[50:53], v[214:217], v[162:165], v[50:53]
	v_mfma_f32_16x16x32_bf16 v[38:41], v[206:209], v[170:173], v[38:41]
	v_mfma_f32_16x16x32_bf16 v[34:37], v[214:217], v[170:173], v[34:37]
	v_mfma_f32_16x16x32_bf16 v[22:25], v[206:209], v[178:181], v[22:25]
	v_mfma_f32_16x16x32_bf16 v[18:21], v[214:217], v[178:181], v[18:21]
	v_mfma_f32_16x16x32_bf16 v[6:9], v[206:209], v[186:189], v[6:9]
	v_mfma_f32_16x16x32_bf16 v[2:5], v[214:217], v[186:189], v[2:5]
	v_mfma_f32_16x16x32_bf16 v[54:57], v[210:213], v[166:169], v[54:57]
	v_mfma_f32_16x16x32_bf16 v[50:53], v[218:221], v[166:169], v[50:53]
	v_mfma_f32_16x16x32_bf16 v[38:41], v[210:213], v[174:177], v[38:41]
	v_mfma_f32_16x16x32_bf16 v[34:37], v[218:221], v[174:177], v[34:37]
	v_mfma_f32_16x16x32_bf16 v[22:25], v[210:213], v[182:185], v[22:25]
	v_mfma_f32_16x16x32_bf16 v[18:21], v[218:221], v[182:185], v[18:21]
	v_mfma_f32_16x16x32_bf16 v[6:9], v[210:213], v[202:205], v[6:9]
	v_mfma_f32_16x16x32_bf16 v[2:5], v[218:221], v[202:205], v[2:5]
	s_setprio 0
	s_add_i32 s51, s51, 2
	s_add_u32 s20, s20, 0x100
	s_addc_u32 s21, s21, 0
	s_add_u32 s45, s45, 0x100
	s_addc_u32 s50, s50, 0
	s_cmp_gt_u32 s51, 13
	s_barrier
	s_cbranch_scc0 .LBB0_1241
	v_readfirstlane_b32 s98, v191
	s_cmpk_gt_u32 s98, 0xff
	s_cbranch_scc1 .Lrl_e0_1241
	s_barrier

.LBB0_1353:
	v_add_u32_e32 v0, s61, v187
	s_waitcnt vmcnt(0)
	ds_read_b128 v[130:133], v0
	ds_read_b128 v[134:137], v0 offset:1024
	ds_read_b128 v[138:141], v0 offset:2048
	ds_read_b128 v[142:145], v0 offset:3072
	s_add_u32 s0, s20, 0xfffc0080
	s_addc_u32 s1, s21, -1
	s_cmp_eq_u32 s26, 12
	s_cselect_b32 s43, s4, s1
	s_cselect_b32 s42, s8, s0
	s_cselect_b32 s35, s10, s25
	s_cselect_b32 s34, s11, s24
	v_lshl_add_u64 v[194:195], s[20:21], 0, v[174:175]
	s_add_i32 m0, s67, 0xc000
	ds_read_b128 v[146:149], v202
	ds_read_b128 v[150:153], v202 offset:1024
	ds_read_b128 v[154:157], v202 offset:2048
	ds_read_b128 v[158:161], v202 offset:3072
	ds_read_b128 v[178:181], v202 offset:4096
	ds_read_b128 v[182:185], v202 offset:5120
	ds_read_b128 v[204:207], v202 offset:6144
	ds_read_b128 v[208:211], v202 offset:7168
	global_load_lds_dwordx4 v[194:195], off
	v_lshl_add_u64 v[194:195], s[20:21], 0, v[176:177]
	s_add_i32 m0, s67, 0xe000
	s_nop 0
	global_load_lds_dwordx4 v[194:195], off
	s_waitcnt lgkmcnt(8)
	s_setprio 1
	s_barrier
	s_waitcnt lgkmcnt(0)
	s_waitcnt lgkmcnt(0)
	v_mfma_f32_16x16x32_bf16 v[126:129], v[130:133], v[146:149], v[126:129]
	v_mfma_f32_16x16x32_bf16 v[122:125], v[138:141], v[146:149], v[122:125]
	v_mfma_f32_16x16x32_bf16 v[118:121], v[130:133], v[154:157], v[118:121]
	v_mfma_f32_16x16x32_bf16 v[114:117], v[138:141], v[154:157], v[114:117]
	v_mfma_f32_16x16x32_bf16 v[102:105], v[130:133], v[178:181], v[102:105]
	v_mfma_f32_16x16x32_bf16 v[98:101], v[138:141], v[178:181], v[98:101]
	v_mfma_f32_16x16x32_bf16 v[86:89], v[130:133], v[204:207], v[86:89]
	v_mfma_f32_16x16x32_bf16 v[82:85], v[138:141], v[204:207], v[82:85]
	v_mfma_f32_16x16x32_bf16 v[126:129], v[134:137], v[150:153], v[126:129]
	v_mfma_f32_16x16x32_bf16 v[122:125], v[142:145], v[150:153], v[122:125]
	v_mfma_f32_16x16x32_bf16 v[118:121], v[134:137], v[158:161], v[118:121]
	v_mfma_f32_16x16x32_bf16 v[114:117], v[142:145], v[158:161], v[114:117]
	v_mfma_f32_16x16x32_bf16 v[102:105], v[134:137], v[182:185], v[102:105]
	v_mfma_f32_16x16x32_bf16 v[98:101], v[142:145], v[182:185], v[98:101]
	v_mfma_f32_16x16x32_bf16 v[86:89], v[134:137], v[208:211], v[86:89]
	v_mfma_f32_16x16x32_bf16 v[82:85], v[142:145], v[208:211], v[82:85]
	s_setprio 0
	s_barrier
	s_mov_b32 m0, s62
	v_add_u32_e32 v0, s78, v187
	v_lshl_add_u64 v[194:195], s[34:35], 0, v[162:163]
	ds_read_b128 v[212:215], v0
	ds_read_b128 v[216:219], v0 offset:1024
	ds_read_b128 v[220:223], v0 offset:2048
	ds_read_b128 v[242:245], v0 offset:3072
	global_load_lds_dwordx4 v[194:195], off
	v_lshl_add_u64 v[196:197], s[34:35], 0, v[164:165]
	s_mov_b32 m0, s63
	s_nop 0
	global_load_lds_dwordx4 v[196:197], off
	s_setprio 1
	s_barrier
	s_waitcnt lgkmcnt(0)
	s_waitcnt lgkmcnt(0)
	v_mfma_f32_16x16x32_bf16 v[110:113], v[212:215], v[146:149], v[110:113]
	v_mfma_f32_16x16x32_bf16 v[106:109], v[220:223], v[146:149], v[106:109]
	v_mfma_f32_16x16x32_bf16 v[94:97], v[212:215], v[154:157], v[94:97]
	v_mfma_f32_16x16x32_bf16 v[90:93], v[220:223], v[154:157], v[90:93]
	v_mfma_f32_16x16x32_bf16 v[78:81], v[212:215], v[178:181], v[78:81]
	v_mfma_f32_16x16x32_bf16 v[74:77], v[220:223], v[178:181], v[74:77]
	v_mfma_f32_16x16x32_bf16 v[70:73], v[212:215], v[204:207], v[70:73]
	v_mfma_f32_16x16x32_bf16 v[66:69], v[220:223], v[204:207], v[66:69]
	v_mfma_f32_16x16x32_bf16 v[110:113], v[216:219], v[150:153], v[110:113]
	v_mfma_f32_16x16x32_bf16 v[106:109], v[242:245], v[150:153], v[106:109]
	v_mfma_f32_16x16x32_bf16 v[94:97], v[216:219], v[158:161], v[94:97]
	v_mfma_f32_16x16x32_bf16 v[90:93], v[242:245], v[158:161], v[90:93]
	v_mfma_f32_16x16x32_bf16 v[78:81], v[216:219], v[182:185], v[78:81]
	v_mfma_f32_16x16x32_bf16 v[74:77], v[242:245], v[182:185], v[74:77]
	v_mfma_f32_16x16x32_bf16 v[70:73], v[216:219], v[208:211], v[70:73]
	v_mfma_f32_16x16x32_bf16 v[66:69], v[242:245], v[208:211], v[66:69]
	s_setprio 0
	s_mov_b32 m0, s67
	v_lshl_add_u64 v[246:247], s[42:43], 0, v[162:163]
	s_barrier
	ds_read_b128 v[146:149], v202 offset:16384
	ds_read_b128 v[150:153], v202 offset:17408
	ds_read_b128 v[154:157], v202 offset:18432
	ds_read_b128 v[158:161], v202 offset:19456
	ds_read_b128 v[178:181], v202 offset:20480
	ds_read_b128 v[182:185], v202 offset:21504
	ds_read_b128 v[204:207], v202 offset:22528
	ds_read_b128 v[208:211], v202 offset:23552
	global_load_lds_dwordx4 v[246:247], off
	v_lshl_add_u64 v[248:249], s[42:43], 0, v[164:165]
	s_mov_b32 m0, s75
	s_nop 0
	global_load_lds_dwordx4 v[248:249], off
	s_setprio 1
	s_barrier
	s_waitcnt lgkmcnt(0)
	s_waitcnt lgkmcnt(0)
	v_mfma_f32_16x16x32_bf16 v[62:65], v[130:133], v[146:149], v[62:65]
	v_mfma_f32_16x16x32_bf16 v[58:61], v[138:141], v[146:149], v[58:61]
	v_mfma_f32_16x16x32_bf16 v[54:57], v[130:133], v[154:157], v[54:57]
	v_mfma_f32_16x16x32_bf16 v[50:53], v[138:141], v[154:157], v[50:53]
	v_mfma_f32_16x16x32_bf16 v[38:41], v[130:133], v[178:181], v[38:41]
	v_mfma_f32_16x16x32_bf16 v[34:37], v[138:141], v[178:181], v[34:37]
	v_mfma_f32_16x16x32_bf16 v[22:25], v[130:133], v[204:207], v[22:25]
	v_mfma_f32_16x16x32_bf16 v[14:17], v[138:141], v[204:207], v[14:17]
	v_mfma_f32_16x16x32_bf16 v[62:65], v[134:137], v[150:153], v[62:65]
	v_mfma_f32_16x16x32_bf16 v[58:61], v[142:145], v[150:153], v[58:61]
	v_mfma_f32_16x16x32_bf16 v[54:57], v[134:137], v[158:161], v[54:57]
	v_mfma_f32_16x16x32_bf16 v[50:53], v[142:145], v[158:161], v[50:53]
	v_mfma_f32_16x16x32_bf16 v[38:41], v[134:137], v[182:185], v[38:41]
	v_mfma_f32_16x16x32_bf16 v[34:37], v[142:145], v[182:185], v[34:37]
	v_mfma_f32_16x16x32_bf16 v[22:25], v[134:137], v[208:211], v[22:25]
	v_mfma_f32_16x16x32_bf16 v[14:17], v[142:145], v[208:211], v[14:17]
	s_setprio 0
	s_barrier
	s_add_u32 s0, s34, 0x40000
	s_addc_u32 s1, s35, 0
	s_mov_b32 m0, s79
	v_lshl_add_u64 v[130:131], s[0:1], 0, v[162:163]
	global_load_lds_dwordx4 v[130:131], off
	v_lshl_add_u64 v[130:131], s[0:1], 0, v[164:165]
	s_mov_b32 m0, s92
	s_nop 0
	global_load_lds_dwordx4 v[130:131], off
	s_waitcnt vmcnt(6)
	s_setprio 1
	s_barrier
	v_mfma_f32_16x16x32_bf16 v[46:49], v[212:215], v[146:149], v[46:49]
	v_mfma_f32_16x16x32_bf16 v[42:45], v[220:223], v[146:149], v[42:45]
	v_mfma_f32_16x16x32_bf16 v[30:33], v[212:215], v[154:157], v[30:33]
	v_mfma_f32_16x16x32_bf16 v[26:29], v[220:223], v[154:157], v[26:29]
	v_mfma_f32_16x16x32_bf16 v[18:21], v[212:215], v[178:181], v[18:21]
	v_mfma_f32_16x16x32_bf16 v[10:13], v[220:223], v[178:181], v[10:13]
	v_mfma_f32_16x16x32_bf16 v[6:9], v[212:215], v[204:207], v[6:9]
	v_mfma_f32_16x16x32_bf16 v[2:5], v[220:223], v[204:207], v[2:5]
	v_mfma_f32_16x16x32_bf16 v[46:49], v[216:219], v[150:153], v[46:49]
	v_mfma_f32_16x16x32_bf16 v[42:45], v[242:245], v[150:153], v[42:45]
	v_mfma_f32_16x16x32_bf16 v[30:33], v[216:219], v[158:161], v[30:33]
	v_mfma_f32_16x16x32_bf16 v[26:29], v[242:245], v[158:161], v[26:29]
	v_mfma_f32_16x16x32_bf16 v[18:21], v[216:219], v[182:185], v[18:21]
	v_mfma_f32_16x16x32_bf16 v[10:13], v[242:245], v[182:185], v[10:13]
	v_mfma_f32_16x16x32_bf16 v[6:9], v[216:219], v[208:211], v[6:9]
	v_mfma_f32_16x16x32_bf16 v[2:5], v[242:245], v[208:211], v[2:5]
	s_setprio 0
	v_add_u32_e32 v0, s80, v187
	s_barrier
	ds_read_b128 v[130:133], v0
	ds_read_b128 v[134:137], v0 offset:1024
	ds_read_b128 v[138:141], v0 offset:2048
	ds_read_b128 v[142:145], v0 offset:3072
	s_add_u32 s0, s42, 0x40000
	s_addc_u32 s1, s43, 0
	s_mov_b32 m0, s93
	v_lshl_add_u64 v[212:213], s[0:1], 0, v[162:163]
	ds_read_b128 v[146:149], v202 offset:32768
	ds_read_b128 v[150:153], v202 offset:33792
	ds_read_b128 v[154:157], v202 offset:34816
	ds_read_b128 v[158:161], v202 offset:35840
	ds_read_b128 v[178:181], v202 offset:36864
	ds_read_b128 v[182:185], v202 offset:37888
	ds_read_b128 v[204:207], v202 offset:38912
	ds_read_b128 v[208:211], v202 offset:39936
	global_load_lds_dwordx4 v[212:213], off
	v_lshl_add_u64 v[212:213], s[0:1], 0, v[164:165]
	s_mov_b32 m0, s60
	s_nop 0
	global_load_lds_dwordx4 v[212:213], off
	s_waitcnt lgkmcnt(8)
	s_setprio 1
	s_barrier
	s_waitcnt lgkmcnt(0)
	s_waitcnt lgkmcnt(0)
	v_mfma_f32_16x16x32_bf16 v[126:129], v[130:133], v[146:149], v[126:129]
	v_mfma_f32_16x16x32_bf16 v[122:125], v[138:141], v[146:149], v[122:125]
	v_mfma_f32_16x16x32_bf16 v[118:121], v[130:133], v[154:157], v[118:121]
	v_mfma_f32_16x16x32_bf16 v[114:117], v[138:141], v[154:157], v[114:117]
	v_mfma_f32_16x16x32_bf16 v[102:105], v[130:133], v[178:181], v[102:105]
	v_mfma_f32_16x16x32_bf16 v[98:101], v[138:141], v[178:181], v[98:101]
	v_mfma_f32_16x16x32_bf16 v[86:89], v[130:133], v[204:207], v[86:89]
	v_mfma_f32_16x16x32_bf16 v[82:85], v[138:141], v[204:207], v[82:85]
	v_mfma_f32_16x16x32_bf16 v[126:129], v[134:137], v[150:153], v[126:129]
	v_mfma_f32_16x16x32_bf16 v[122:125], v[142:145], v[150:153], v[122:125]
	v_mfma_f32_16x16x32_bf16 v[118:121], v[134:137], v[158:161], v[118:121]
	v_mfma_f32_16x16x32_bf16 v[114:117], v[142:145], v[158:161], v[114:117]
	v_mfma_f32_16x16x32_bf16 v[102:105], v[134:137], v[182:185], v[102:105]
	v_mfma_f32_16x16x32_bf16 v[98:101], v[142:145], v[182:185], v[98:101]
	v_mfma_f32_16x16x32_bf16 v[86:89], v[134:137], v[208:211], v[86:89]
	v_mfma_f32_16x16x32_bf16 v[82:85], v[142:145], v[208:211], v[82:85]
	s_setprio 0
	s_barrier
	s_mov_b32 m0, s81
	v_add_u32_e32 v0, s14, v187
	v_lshl_add_u64 v[194:195], v[194:195], 0, s[88:89]
	ds_read_b128 v[212:215], v0
	ds_read_b128 v[216:219], v0 offset:1024
	ds_read_b128 v[220:223], v0 offset:2048
	ds_read_b128 v[242:245], v0 offset:3072
	global_load_lds_dwordx4 v[194:195], off
	v_lshl_add_u64 v[194:195], v[196:197], 0, s[88:89]
	s_mov_b32 m0, s68
	s_nop 0
	global_load_lds_dwordx4 v[194:195], off
	s_setprio 1
	s_barrier
	s_waitcnt lgkmcnt(0)
	s_waitcnt lgkmcnt(0)
	v_mfma_f32_16x16x32_bf16 v[110:113], v[212:215], v[146:149], v[110:113]
	v_mfma_f32_16x16x32_bf16 v[106:109], v[220:223], v[146:149], v[106:109]
	v_mfma_f32_16x16x32_bf16 v[94:97], v[212:215], v[154:157], v[94:97]
	v_mfma_f32_16x16x32_bf16 v[90:93], v[220:223], v[154:157], v[90:93]
	v_mfma_f32_16x16x32_bf16 v[78:81], v[212:215], v[178:181], v[78:81]
	v_mfma_f32_16x16x32_bf16 v[74:77], v[220:223], v[178:181], v[74:77]
	v_mfma_f32_16x16x32_bf16 v[70:73], v[212:215], v[204:207], v[70:73]
	v_mfma_f32_16x16x32_bf16 v[66:69], v[220:223], v[204:207], v[66:69]
	v_mfma_f32_16x16x32_bf16 v[110:113], v[216:219], v[150:153], v[110:113]
	v_mfma_f32_16x16x32_bf16 v[106:109], v[242:245], v[150:153], v[106:109]
	v_mfma_f32_16x16x32_bf16 v[94:97], v[216:219], v[158:161], v[94:97]
	v_mfma_f32_16x16x32_bf16 v[90:93], v[242:245], v[158:161], v[90:93]
	v_mfma_f32_16x16x32_bf16 v[78:81], v[216:219], v[182:185], v[78:81]
	v_mfma_f32_16x16x32_bf16 v[74:77], v[242:245], v[182:185], v[74:77]
	v_mfma_f32_16x16x32_bf16 v[70:73], v[216:219], v[208:211], v[70:73]
	v_mfma_f32_16x16x32_bf16 v[66:69], v[242:245], v[208:211], v[66:69]
	s_setprio 0
	s_mov_b32 m0, s69
	v_lshl_add_u64 v[194:195], v[246:247], 0, s[88:89]
	s_barrier
	ds_read_b128 v[146:149], v202 offset:49152
	ds_read_b128 v[150:153], v202 offset:50176
	ds_read_b128 v[154:157], v202 offset:51200
	ds_read_b128 v[158:161], v202 offset:52224
	ds_read_b128 v[178:181], v202 offset:53248
	ds_read_b128 v[182:185], v202 offset:54272
	ds_read_b128 v[204:207], v202 offset:55296
	ds_read_b128 v[208:211], v202 offset:56320
	global_load_lds_dwordx4 v[194:195], off
	v_lshl_add_u64 v[194:195], v[248:249], 0, s[88:89]
	s_mov_b32 m0, s19
	s_nop 0
	global_load_lds_dwordx4 v[194:195], off
	s_setprio 1
	s_barrier
	s_waitcnt lgkmcnt(0)
	s_waitcnt lgkmcnt(0)
	v_mfma_f32_16x16x32_bf16 v[62:65], v[130:133], v[146:149], v[62:65]
	v_mfma_f32_16x16x32_bf16 v[58:61], v[138:141], v[146:149], v[58:61]
	v_mfma_f32_16x16x32_bf16 v[54:57], v[130:133], v[154:157], v[54:57]
	v_mfma_f32_16x16x32_bf16 v[50:53], v[138:141], v[154:157], v[50:53]
	v_mfma_f32_16x16x32_bf16 v[38:41], v[130:133], v[178:181], v[38:41]
	v_mfma_f32_16x16x32_bf16 v[34:37], v[138:141], v[178:181], v[34:37]
	v_mfma_f32_16x16x32_bf16 v[22:25], v[130:133], v[204:207], v[22:25]
	v_mfma_f32_16x16x32_bf16 v[14:17], v[138:141], v[204:207], v[14:17]
	v_mfma_f32_16x16x32_bf16 v[62:65], v[134:137], v[150:153], v[62:65]
	v_mfma_f32_16x16x32_bf16 v[58:61], v[142:145], v[150:153], v[58:61]
	v_mfma_f32_16x16x32_bf16 v[54:57], v[134:137], v[158:161], v[54:57]
	v_mfma_f32_16x16x32_bf16 v[50:53], v[142:145], v[158:161], v[50:53]
	v_mfma_f32_16x16x32_bf16 v[38:41], v[134:137], v[182:185], v[38:41]
	v_mfma_f32_16x16x32_bf16 v[34:37], v[142:145], v[182:185], v[34:37]
	v_mfma_f32_16x16x32_bf16 v[22:25], v[134:137], v[208:211], v[22:25]
	v_mfma_f32_16x16x32_bf16 v[14:17], v[142:145], v[208:211], v[14:17]
	s_setprio 0
	s_barrier
	s_add_u32 s0, s34, 0x40080
	s_addc_u32 s1, s35, 0
	s_mov_b32 m0, s15
	v_lshl_add_u64 v[130:131], s[0:1], 0, v[162:163]
	global_load_lds_dwordx4 v[130:131], off
	v_lshl_add_u64 v[130:131], s[0:1], 0, v[164:165]
	s_mov_b32 m0, s16
	s_nop 0
	global_load_lds_dwordx4 v[130:131], off
	s_waitcnt vmcnt(6)
	s_setprio 1
	s_barrier
	v_mfma_f32_16x16x32_bf16 v[46:49], v[212:215], v[146:149], v[46:49]
	v_mfma_f32_16x16x32_bf16 v[42:45], v[220:223], v[146:149], v[42:45]
	v_mfma_f32_16x16x32_bf16 v[30:33], v[212:215], v[154:157], v[30:33]
	v_mfma_f32_16x16x32_bf16 v[26:29], v[220:223], v[154:157], v[26:29]
	v_mfma_f32_16x16x32_bf16 v[18:21], v[212:215], v[178:181], v[18:21]
	v_mfma_f32_16x16x32_bf16 v[10:13], v[220:223], v[178:181], v[10:13]
	v_mfma_f32_16x16x32_bf16 v[6:9], v[212:215], v[204:207], v[6:9]
	v_mfma_f32_16x16x32_bf16 v[2:5], v[220:223], v[204:207], v[2:5]
	v_mfma_f32_16x16x32_bf16 v[46:49], v[216:219], v[150:153], v[46:49]
	v_mfma_f32_16x16x32_bf16 v[42:45], v[242:245], v[150:153], v[42:45]
	v_mfma_f32_16x16x32_bf16 v[30:33], v[216:219], v[158:161], v[30:33]
	v_mfma_f32_16x16x32_bf16 v[26:29], v[242:245], v[158:161], v[26:29]
	v_mfma_f32_16x16x32_bf16 v[18:21], v[216:219], v[182:185], v[18:21]
	v_mfma_f32_16x16x32_bf16 v[10:13], v[242:245], v[182:185], v[10:13]
	v_mfma_f32_16x16x32_bf16 v[6:9], v[216:219], v[208:211], v[6:9]
	v_mfma_f32_16x16x32_bf16 v[2:5], v[242:245], v[208:211], v[2:5]
	s_setprio 0
	s_add_i32 s26, s26, 2
	s_add_u32 s20, s20, 0x100
	s_addc_u32 s21, s21, 0
	s_add_u32 s24, s24, 0x100
	s_addc_u32 s25, s25, 0
	s_cmp_gt_u32 s26, 13
	s_barrier
	s_cbranch_scc0 .LBB0_1353
	v_readfirstlane_b32 s98, v191
	s_cmpk_gt_u32 s98, 0xff
	s_cbranch_scc1 .Lrl_e0_1353
	s_barrier
